# v11
# speedup vs baseline: 1.2948x; 1.0161x over previous
.LBB0_243:
	v_med3_f32 v3, v48, s87, v198
	v_med3_f32 v10, v58, s87, v198
	v_exp_f32_e32 v4, v3
	s_nop 7
	v_med3_f32 v3, v49, s87, v198
	v_exp_f32_e32 v131, v10
	v_med3_f32 v10, v59, s87, v198
	v_exp_f32_e32 v5, v3
	v_med3_f32 v3, v50, s87, v198
	v_exp_f32_e32 v132, v10
	v_med3_f32 v10, v60, s87, v198
	v_exp_f32_e32 v3, v3
	v_med3_f32 v6, v51, s87, v198
	v_exp_f32_e32 v12, v10
	v_med3_f32 v10, v61, s87, v198
	v_exp_f32_e32 v128, v6
	v_exp_f32_e32 v13, v10
	v_med3_f32 v10, v62, s87, v198
	v_med3_f32 v6, v52, s87, v198
	v_med3_f32 v7, v53, s87, v198
	v_exp_f32_e32 v60, v10
	v_med3_f32 v10, v63, s87, v198
	v_exp_f32_e32 v6, v6
	v_exp_f32_e32 v7, v7
	v_med3_f32 v8, v54, s87, v198
	v_exp_f32_e32 v61, v10
	v_pk_add_f32 v[10:11], v[4:5], 1.0 op_sel_hi:[1,0]
	v_exp_f32_e32 v129, v8
	v_med3_f32 v8, v55, s87, v198
	v_mul_f32_e32 v11, v10, v11
	v_add_f32_e32 v14, 1.0, v3
	v_exp_f32_e32 v130, v8
	v_mul_f32_e32 v62, v14, v11
	v_add_f32_e32 v14, 1.0, v128
	v_med3_f32 v8, v56, s87, v198
	v_med3_f32 v9, v57, s87, v198
	v_mul_f32_e32 v14, v14, v62
	v_exp_f32_e32 v8, v8
	v_exp_f32_e32 v9, v9
	v_rcp_f32_e32 v63, v14
	v_pk_add_f32 v[14:15], v[6:7], 1.0 op_sel_hi:[1,0]
	v_add_f32_e32 v48, 1.0, v129
	v_mul_f32_e32 v15, v14, v15
	v_mul_f32_e32 v133, v48, v15
	v_add_f32_e32 v48, 1.0, v130
	v_mul_f32_e32 v48, v48, v133
	v_rcp_f32_e32 v134, v48
	v_pk_add_f32 v[48:49], v[8:9], 1.0 op_sel_hi:[1,0]
	v_add_f32_e32 v50, 1.0, v131
	v_mul_f32_e32 v49, v48, v49
	v_mul_f32_e32 v135, v50, v49
	v_add_f32_e32 v50, 1.0, v132
	v_mul_f32_e32 v50, v50, v135
	v_rcp_f32_e32 v136, v50
	v_pk_add_f32 v[50:51], v[12:13], 1.0 op_sel_hi:[1,0]
	v_add_f32_e32 v52, 1.0, v60
	v_mul_f32_e32 v51, v50, v51
	v_mul_f32_e32 v137, v52, v51
	v_add_f32_e32 v52, 1.0, v61
	v_mul_f32_e32 v52, v52, v137
	v_rcp_f32_e32 v138, v52
	v_mov_b32_e32 v56, v134
	v_mov_b32_e32 v58, v134
	v_mov_b32_e32 v52, v63
	v_mov_b32_e32 v57, v138
	v_mov_b32_e32 v59, v138
	v_mov_b32_e32 v54, v63
	v_permlane32_swap_b32_e32 v56, v58
	v_mov_b32_e32 v53, v136
	v_mov_b32_e32 v55, v136
	v_permlane32_swap_b32_e32 v57, v59
	v_permlane32_swap_b32_e32 v52, v54
	v_permlane32_swap_b32_e32 v53, v55
	v_pk_mul_f32 v[56:57], v[56:57], v[58:59]
	v_pk_mul_f32 v[52:53], v[52:53], v[54:55]
	v_mul_f32_e32 v139, v127, v57
	v_mul_f32_e32 v140, v53, v139
	v_mul_f32_e32 v141, v56, v140
	v_cndmask_b32_e64 v54, 1.0, v54, s[6:7]
	v_mul_f32_e32 v54, v54, v141
	v_mul_f32_e32 v54, v63, v54
	v_mul_f32_e32 v63, v4, v54
	v_mul_f32_e32 v4, v5, v54
	v_mul_f32_e32 v10, v10, v4
	v_mul_f32_e32 v3, v3, v54
	v_mul_f32_e32 v4, v128, v54
	v_mul_f32_e32 v3, v11, v3
	v_mul_f32_e32 v11, v62, v4
	v_cndmask_b32_e64 v4, 1.0, v58, s[6:7]
	v_mul_f32_e32 v4, v4, v140
	v_mul_f32_e32 v4, v134, v4
	v_mul_f32_e32 v5, v7, v4
	v_mul_f32_e32 v54, v6, v4
	v_mul_f32_e32 v14, v14, v5
	v_mul_f32_e32 v5, v129, v4
	v_mul_f32_e32 v4, v130, v4
	v_mul_f32_e32 v58, v133, v4
	v_cndmask_b32_e64 v4, 1.0, v55, s[6:7]
	v_mul_f32_e32 v4, v4, v139
	v_mul_f32_e32 v4, v136, v4
	v_mul_f32_e32 v15, v15, v5
	v_mul_f32_e32 v5, v9, v4
	v_mul_f32_e32 v55, v8, v4
	v_mul_f32_e32 v48, v48, v5
	v_mul_f32_e32 v5, v131, v4
	v_mul_f32_e32 v4, v132, v4
	v_mul_f32_e32 v62, v135, v4
	v_cndmask_b32_e64 v4, 1.0, v59, s[6:7]
	v_mul_f32_e32 v4, v127, v4
	s_nop 0
	v_mul_f32_e32 v49, v49, v5
	v_mul_f32_e32 v59, v4, v138
	s_nop 0
	v_cvt_pk_bf16_f32 v8, v63, v10
	v_cvt_pk_bf16_f32 v10, v54, v14
	s_nop 0
	v_cvt_pk_bf16_f32 v9, v3, v11
	v_cvt_pk_bf16_f32 v11, v15, v58
	v_mul_f32_e32 v127, v12, v59
	s_waitcnt lgkmcnt(0)
	v_mfma_f32_32x32x16_bf16 v[16:31], v[8:11], v[228:231], v[16:31]
	s_nop 0
	v_mul_f32_e32 v12, v60, v59
	v_mul_f32_e32 v15, v51, v12
	v_mul_f32_e32 v12, v61, v59
	v_mul_f32_e32 v3, v13, v59
	v_mul_f32_e32 v3, v50, v3
	s_waitcnt lgkmcnt(0)
	v_mfma_f32_32x32x16_bf16 v[32:47], v[8:11], v[232:235], v[32:47]
	s_nop 0
	v_mul_f32_e32 v11, v137, v12
	v_cvt_pk_bf16_f32 v8, v55, v48
	v_cvt_pk_bf16_f32 v9, v49, v62
	v_cvt_pk_bf16_f32 v10, v127, v3
	v_cvt_pk_bf16_f32 v11, v15, v11
	v_mul_f32_e64 v12, v52, v56
	v_mul_f32_e64 v13, v53, v57
	s_waitcnt lgkmcnt(0)
	v_mfma_f32_32x32x16_bf16 v[16:31], v[8:11], v[236:239], v[16:31]
	s_nop 0
	v_mul_f32_e32 v3, v12, v13
	v_log_f32_e32 v3, v3
	s_nop 0
	v_add_f32_e32 v111, v111, v3
	s_waitcnt lgkmcnt(0)
	v_mfma_f32_32x32x16_bf16 v[32:47], v[8:11], v[240:243], v[32:47]
	v_exp_f32_e32 v127, v111

.LBB0_245:
	s_cmp_gt_i32 s2, s47
	s_cbranch_scc1 .LBB0_244
	ds_read_b128 v[4:7], v2
	ds_read_b128 v[228:231], v2 offset:32
	ds_read_b128 v[232:235], v2 offset:64
	ds_read_b128 v[236:239], v2 offset:96
	v_add_u32_e32 v244, s59, v0
	v_add_u32_e32 v245, 0x2000, v244
	s_cmp_lg_u32 s47, s2
	s_waitcnt lgkmcnt(3)
	v_mfma_f32_32x32x16_bf16 v[48:63], v[4:7], v[64:67], 0
	s_waitcnt lgkmcnt(2)
	v_mfma_f32_32x32x16_bf16 v[48:63], v[228:231], v[68:71], v[48:63]
	s_waitcnt lgkmcnt(1)
	v_mfma_f32_32x32x16_bf16 v[48:63], v[232:235], v[76:79], v[48:63]
	s_waitcnt lgkmcnt(0)
	v_mfma_f32_32x32x16_bf16 v[48:63], v[236:239], v[80:83], v[48:63]
	ds_read2_b64 v[228:231], v244 offset1:2
	ds_read2_b64 v[232:235], v245 offset0:64 offset1:66
	ds_read2_b64 v[236:239], v244 offset0:4 offset1:6
	ds_read2_b64 v[240:243], v245 offset0:68 offset1:70
	s_cbranch_scc1 .LBB0_243
	s_nop 10
	v_cndmask_b32_e64 v48, v197, v48, s[8:9]
	v_cndmask_b32_e64 v49, v197, v49, s[10:11]
	v_cndmask_b32_e64 v50, v197, v50, s[12:13]
	v_cndmask_b32_e64 v51, v197, v51, s[14:15]
	v_cndmask_b32_e64 v52, v197, v52, s[16:17]
	v_cndmask_b32_e64 v53, v197, v53, s[18:19]
	v_cndmask_b32_e64 v54, v197, v54, s[20:21]
	v_cndmask_b32_e64 v55, v197, v55, s[22:23]
	v_cndmask_b32_e64 v56, v197, v56, s[24:25]
	v_cndmask_b32_e64 v57, v197, v57, s[26:27]
	v_cndmask_b32_e64 v58, v197, v58, s[28:29]
	v_cndmask_b32_e64 v59, v197, v59, s[30:31]
	v_cndmask_b32_e64 v60, v197, v60, s[34:35]
	v_cndmask_b32_e64 v61, v197, v61, s[36:37]
	v_cndmask_b32_e64 v62, v197, v62, s[38:39]
	v_cndmask_b32_e64 v63, v197, v63, s[40:41]
	s_branch .LBB0_243

.LBB0_261:
	s_lshl_b32 s23, s2, 6
	v_mov_b32_e32 v2, v178
	s_cmp_ge_i32 s72, s23
	v_readfirstlane_b32 s6, v2
	s_cbranch_scc1 .LBB0_284
	s_ashr_i32 s14, s6, 6
	v_bfe_u32 v0, v2, 3, 3
	v_lshl_or_b32 v0, s14, 3, v0
	v_lshrrev_b32_e32 v3, 1, v0
	v_xor_b32_e32 v3, v3, v2
	v_lshlrev_b32_e32 v3, 4, v3
	v_lshlrev_b32_e32 v0, 11, v0
	s_movk_i32 s7, 0x70
	s_lshl_b32 s27, s2, 2
	v_and_or_b32 v173, v3, s7, v0
	v_bfe_u32 v248, v178, 3, 3
	s_and_b32 s8, s14, 1
	s_lshl_b32 s8, s8, 5
	s_lshr_b32 s9, s14, 1
	s_add_i32 s8, s8, s9
	v_lshl_add_u32 v248, v248, 2, s8
	v_lshlrev_b32_e32 v248, 11, v248
	v_and_b32_e32 v249, 0x70, v173
	v_or_b32_e32 v248, v248, v249
	v_cvt_f32_ubyte0_e32 v0, s27
	v_rcp_iflag_f32_e32 v0, v0
	s_lshl_b32 s26, s2, 3
	v_readlane_b32 s2, v227, 9
	s_ashr_i32 s7, s6, 1
	v_mul_f32_e32 v0, 0x4f7ffffe, v0
	v_cvt_u32_f32_e32 v0, v0
	s_and_b32 s25, s6, 0xc0
	s_or_b32 s2, s26, s2
	v_readlane_b32 s6, v227, 12
	s_sub_i32 s8, 0, s27
	v_readfirstlane_b32 s9, v0
	s_mul_i32 s2, s2, s6
	v_readlane_b32 s6, v227, 37
	s_mul_i32 s8, s8, s9
	s_add_i32 s2, s2, s6
	s_mul_hi_u32 s8, s9, s8
	s_and_b32 s24, s7, 0xffffff80
	s_abs_i32 s7, s2
	s_add_i32 s28, s9, s8
	s_mul_hi_u32 s8, s7, s28
	s_mul_i32 s9, s8, s27
	s_sub_i32 s7, s7, s9
	s_ashr_i32 s6, s2, 31
	s_add_i32 s9, s8, 1
	s_sub_i32 s10, s7, s27
	s_cmp_ge_u32 s7, s27
	s_cselect_b32 s8, s9, s8
	s_cselect_b32 s7, s10, s7
	s_add_i32 s9, s8, 1
	s_cmp_ge_u32 s7, s27
	s_cselect_b32 s7, s9, s8
	s_xor_b32 s7, s7, s6
	s_sub_i32 s6, s7, s6
	s_lshl_b32 s8, s6, 2
	s_sub_i32 s7, 64, s8
	s_min_i32 s9, s7, 4
	v_cvt_f32_i32_e32 v0, s9
	s_mul_i32 s6, s6, s27
	s_sub_i32 s2, s2, s6
	s_sext_i32_i8 s6, s2
	v_cvt_f32_i32_e32 v3, s6
	v_rcp_iflag_f32_e32 v4, v0
	s_xor_b32 s6, s6, s9
	s_ashr_i32 s6, s6, 30
	s_or_b32 s10, s6, 1
	v_mul_f32_e32 v4, v3, v4
	v_trunc_f32_e32 v4, v4
	v_fma_f32 v3, -v4, v0, v3
	v_cvt_i32_f32_e32 v4, v4
	v_cmp_ge_f32_e64 s[6:7], |v3|, |v0|
	s_and_b64 s[6:7], s[6:7], exec
	s_cselect_b32 s6, s10, 0
	v_readfirstlane_b32 s7, v4
	s_add_i32 s6, s7, s6
	s_sext_i32_i8 s7, s6
	s_mul_i32 s6, s6, s9
	s_sub_i32 s2, s2, s6
	s_sext_i32_i8 s2, s2
	s_add_i32 s8, s8, s2
	s_lshl_b32 s6, s8, 8
	s_lshl_b32 s8, s7, 8
	s_ashr_i32 s7, s6, 31
	s_lshl_b64 s[6:7], s[6:7], 11
	s_add_u32 s64, s94, s6
	s_addc_u32 s2, s95, s7
	s_ashr_i32 s9, s8, 31
	s_lshl_b64 s[6:7], s[8:9], 11
	s_add_u32 s8, s38, s6
	s_addc_u32 s6, s39, s7
	s_lshl_b32 s29, s14, 10
	s_and_b32 s65, s2, 0xffff
	s_add_i32 s30, s29, 0x8000
	s_mov_b32 m0, s29
	s_and_b32 s9, s6, 0xffff
	s_mov_b32 s10, s66
	s_mov_b32 s11, s67
	buffer_load_dwordx4 v173, s[64:67], 0 offen lds
	s_mov_b32 m0, s30
	s_add_i32 s31, s29, 0x2000
	buffer_load_dwordx4 v248, s[8:11], 0 offen lds
	s_mov_b32 m0, s31
	s_add_i32 s34, s29, 0xa000
	buffer_load_dwordx4 v173, s[64:67], s67 offen lds
	s_mov_b32 m0, s34
	s_add_i32 s35, s29, 0x4000
	buffer_load_dwordx4 v248, s[8:11], s67 offen lds
	s_mov_b32 m0, s35
	s_add_i32 s40, s29, 0xc000
	buffer_load_dwordx4 v173, s[64:67], s83 offen lds
	s_mov_b32 m0, s40
	s_add_i32 s41, s29, 0x6000
	buffer_load_dwordx4 v248, s[8:11], s83 offen lds
	s_mov_b32 m0, s41
	s_add_i32 s46, s29, 0xe000
	buffer_load_dwordx4 v173, s[64:67], s90 offen lds
	s_mov_b32 m0, s46
	v_and_b32_e32 v4, 15, v2
	buffer_load_dwordx4 v248, s[8:11], s90 offen lds
	v_or_b32_e32 v0, s25, v4
	v_lshlrev_b32_e32 v0, 7, v0
	v_and_b32_e32 v3, 0x6400, v0
	v_bfe_u32 v5, v2, 4, 2
	v_lshrrev_b32_e32 v0, 1, v2
	v_bitop3_b32 v6, v5, v0, 7 bitop3:0x78
	v_lshlrev_b32_e32 v0, 7, v2
	v_and_b32_e32 v7, 0x380, v0
	v_or_b32_e32 v0, s24, v4
	v_and_b32_e32 v9, 1, v2
	v_readlane_b32 s8, v227, 53
	v_lshlrev_b32_e32 v8, 7, v0
	v_lshlrev_b32_e32 v0, 5, v9
	v_readlane_b32 s9, v227, 54
	v_lshl_or_b32 v6, v6, 4, v7
	s_mov_b32 s2, 0x8000
	v_lshl_add_u64 v[170:171], s[8:9], 0, v[0:1]
	v_lshlrev_b32_e32 v0, 5, v2
	v_and_b32_e32 v0, 32, v0
	v_ashrrev_i32_e32 v201, 1, v2
	v_or3_b32 v202, v3, v6, s2
	v_lshl_add_u64 v[174:175], s[8:9], 0, v[0:1]
	s_mul_i32 s2, s22, 12
	s_movk_i32 s8, 0xc400
	s_mov_b32 s47, 0
	s_or_b32 s48, s26, 1
	v_cmp_eq_u32_e64 s[6:7], 0, v9
	v_lshlrev_b32_e32 v172, 2, v5
	v_or_b32_e32 v203, 0xfffffa00, v4
	v_lshl_add_u32 v204, v201, 2, v199
	v_and_or_b32 v205, v8, s8, v6
	v_lshlrev_b32_e32 v176, 1, v4
	s_lshl_b32 s14, s2, 1
	s_mov_b32 s49, s72
	s_branch .LBB0_265

.LBB0_271:
	s_cmp_eq_u32 s21, 0x60800
	s_mov_b32 s2, 0x10000
	s_and_b32 s2, s19, 0x10000
	s_xor_b32 s10, s2, 0x10000
	s_add_i32 s51, s29, s10
	s_add_i32 s52, s21, 0xfffa0000
	s_add_i32 s53, s51, 0x8000
	s_mov_b32 s10, s66
	s_mov_b32 s11, s67
	s_waitcnt lgkmcnt(0)
	v_add_u32_e32 v228, s2, v205
	v_add_u32_e32 v229, s2, v202
	ds_read_b128 v[130:133], v229 offset:0
	ds_read_b128 v[134:137], v229 offset:0x800
	ds_read_b128 v[138:141], v229 offset:0x1000
	ds_read_b128 v[142:145], v229 offset:0x1800
	ds_read_b128 v[146:149], v228 offset:0
	ds_read_b128 v[150:153], v228 offset:0x800
	s_setprio 1
	s_mov_b32 m0, s51
	s_nop 0
	buffer_load_dwordx4 v173, s[64:67], s52 offen lds
	s_mov_b32 m0, s53
	s_nop 0
	buffer_load_dwordx4 v248, s[8:11], s52 offen lds
	s_add_i32 m0, s51, 0x2000
	s_add_i32 s52, s21, 0xfffc0000
	buffer_load_dwordx4 v173, s[64:67], s52 offen lds
	s_add_i32 m0, s51, 0xa000
	s_nop 0
	buffer_load_dwordx4 v248, s[8:11], s52 offen lds
	ds_read_b128 v[154:157], v228 offset:0x1000
	v_xor_b32_e32 v177, 64, v228
	s_branch .Lrot2_mid_l
.Lrot2_top_l:
	s_and_b32 s2, s19, 0x10000
	s_xor_b32 s10, s2, 0x10000
	s_add_i32 s51, s29, s10
	s_add_i32 s52, s21, 0xfffa0000
	s_add_i32 s53, s51, 0x8000
	s_mov_b32 s10, s66
	s_mov_b32 s11, s67
	v_add_u32_e32 v228, s2, v205
	v_add_u32_e32 v229, s2, v202
	ds_read_b128 v[130:133], v229 offset:0
	ds_read_b128 v[134:137], v229 offset:0x800
	ds_read_b128 v[138:141], v229 offset:0x1000
	ds_read_b128 v[142:145], v229 offset:0x1800
	ds_read_b128 v[146:149], v228 offset:0
	ds_read_b128 v[150:153], v228 offset:0x800
	s_setprio 1
	s_mov_b32 m0, s51
	s_nop 0
	buffer_load_dwordx4 v173, s[64:67], s52 offen lds
	s_mov_b32 m0, s53
	s_nop 0
	buffer_load_dwordx4 v248, s[8:11], s52 offen lds
	v_mfma_f32_16x16x32_bf16 v[46:49], v[236:239], v[154:157], v[46:49]
	v_mfma_f32_16x16x32_bf16 v[42:45], v[236:239], v[158:161], v[42:45]
	v_mfma_f32_16x16x32_bf16 v[38:41], v[236:239], v[162:165], v[38:41]
	v_mfma_f32_16x16x32_bf16 v[34:37], v[236:239], v[232:235], v[34:37]
	s_add_i32 m0, s51, 0x2000
	s_add_i32 s52, s21, 0xfffc0000
	buffer_load_dwordx4 v173, s[64:67], s52 offen lds
	v_mfma_f32_16x16x32_bf16 v[30:33], v[240:243], v[154:157], v[30:33]
	v_mfma_f32_16x16x32_bf16 v[26:29], v[240:243], v[158:161], v[26:29]
	v_mfma_f32_16x16x32_bf16 v[22:25], v[240:243], v[162:165], v[22:25]
	v_mfma_f32_16x16x32_bf16 v[18:21], v[240:243], v[232:235], v[18:21]
	s_add_i32 m0, s51, 0xa000
	s_nop 0
	buffer_load_dwordx4 v248, s[8:11], s52 offen lds
	v_mfma_f32_16x16x32_bf16 v[14:17], v[244:247], v[154:157], v[14:17]
	v_mfma_f32_16x16x32_bf16 v[10:13], v[244:247], v[158:161], v[10:13]
	v_mfma_f32_16x16x32_bf16 v[6:9], v[244:247], v[162:165], v[6:9]
	v_mfma_f32_16x16x32_bf16 v[2:5], v[244:247], v[232:235], v[2:5]
	ds_read_b128 v[154:157], v228 offset:0x1000
	v_xor_b32_e32 v177, 64, v228
.Lrot2_mid_l:
	s_waitcnt lgkmcnt(2)
	s_nop 0
	v_mfma_f32_16x16x32_bf16 v[122:125], v[146:149], v[130:133], v[122:125]
	v_mfma_f32_16x16x32_bf16 v[126:129], v[146:149], v[134:137], v[126:129]
	v_mfma_f32_16x16x32_bf16 v[118:121], v[146:149], v[138:141], v[118:121]
	v_mfma_f32_16x16x32_bf16 v[114:117], v[146:149], v[142:145], v[114:117]
	s_add_i32 m0, s51, 0x4000
	s_add_i32 s52, s21, 0xfffe0000
	buffer_load_dwordx4 v173, s[64:67], s52 offen lds
	ds_read_b128 v[146:149], v228 offset:0x1800
	s_waitcnt lgkmcnt(2)
	s_nop 0
	v_mfma_f32_16x16x32_bf16 v[110:113], v[150:153], v[130:133], v[110:113]
	v_mfma_f32_16x16x32_bf16 v[106:109], v[150:153], v[134:137], v[106:109]
	v_mfma_f32_16x16x32_bf16 v[102:105], v[150:153], v[138:141], v[102:105]
	v_mfma_f32_16x16x32_bf16 v[98:101], v[150:153], v[142:145], v[98:101]
	s_add_i32 m0, s51, 0xc000
	s_nop 0
	buffer_load_dwordx4 v248, s[8:11], s52 offen lds
	ds_read_b128 v[150:153], v228 offset:0x2000
	s_waitcnt lgkmcnt(2)
	s_nop 0
	v_mfma_f32_16x16x32_bf16 v[94:97], v[154:157], v[130:133], v[94:97]
	v_mfma_f32_16x16x32_bf16 v[90:93], v[154:157], v[134:137], v[90:93]
	v_mfma_f32_16x16x32_bf16 v[86:89], v[154:157], v[138:141], v[86:89]
	v_mfma_f32_16x16x32_bf16 v[82:85], v[154:157], v[142:145], v[82:85]
	s_add_i32 m0, s51, 0x6000
	s_nop 0
	buffer_load_dwordx4 v173, s[64:67], s21 offen lds
	ds_read_b128 v[154:157], v228 offset:0x2800
	s_waitcnt lgkmcnt(2)
	s_nop 0
	v_mfma_f32_16x16x32_bf16 v[78:81], v[146:149], v[130:133], v[78:81]
	v_mfma_f32_16x16x32_bf16 v[74:77], v[146:149], v[134:137], v[74:77]
	v_mfma_f32_16x16x32_bf16 v[70:73], v[146:149], v[138:141], v[70:73]
	v_mfma_f32_16x16x32_bf16 v[66:69], v[146:149], v[142:145], v[66:69]
	s_add_i32 m0, s51, 0xe000
	s_nop 0
	buffer_load_dwordx4 v248, s[8:11], s21 offen lds
	ds_read_b128 v[146:149], v228 offset:0x3000
	s_waitcnt lgkmcnt(2)
	s_nop 0
	v_mfma_f32_16x16x32_bf16 v[62:65], v[150:153], v[130:133], v[62:65]
	v_mfma_f32_16x16x32_bf16 v[58:61], v[150:153], v[134:137], v[58:61]
	v_mfma_f32_16x16x32_bf16 v[54:57], v[150:153], v[138:141], v[54:57]
	v_mfma_f32_16x16x32_bf16 v[50:53], v[150:153], v[142:145], v[50:53]
	ds_read_b128 v[150:153], v228 offset:0x3800
	s_waitcnt lgkmcnt(2)
	v_xor_b32_e32 v0, 64, v229
	v_mfma_f32_16x16x32_bf16 v[46:49], v[154:157], v[130:133], v[46:49]
	v_mfma_f32_16x16x32_bf16 v[42:45], v[154:157], v[134:137], v[42:45]
	v_mfma_f32_16x16x32_bf16 v[38:41], v[154:157], v[138:141], v[38:41]
	v_mfma_f32_16x16x32_bf16 v[34:37], v[154:157], v[142:145], v[34:37]
	ds_read_b128 v[154:157], v0 offset:0
	ds_read_b128 v[158:161], v0 offset:0x800
	ds_read_b128 v[162:165], v0 offset:0x1000
	s_waitcnt lgkmcnt(4)
	s_nop 0
	v_mfma_f32_16x16x32_bf16 v[30:33], v[146:149], v[130:133], v[30:33]
	v_mfma_f32_16x16x32_bf16 v[26:29], v[146:149], v[134:137], v[26:29]
	v_mfma_f32_16x16x32_bf16 v[22:25], v[146:149], v[138:141], v[22:25]
	v_mfma_f32_16x16x32_bf16 v[18:21], v[146:149], v[142:145], v[18:21]
	ds_read_b128 v[232:235], v0 offset:0x1800
	ds_read_b128 v[166:169], v177 offset:0
	ds_read_b128 v[206:209], v177 offset:0x800
	s_waitcnt lgkmcnt(6)
	s_nop 0
	v_mfma_f32_16x16x32_bf16 v[14:17], v[150:153], v[130:133], v[14:17]
	v_mfma_f32_16x16x32_bf16 v[10:13], v[150:153], v[134:137], v[10:13]
	v_mfma_f32_16x16x32_bf16 v[6:9], v[150:153], v[138:141], v[6:9]
	v_mfma_f32_16x16x32_bf16 v[2:5], v[150:153], v[142:145], v[2:5]
	ds_read_b128 v[130:133], v177 offset:0x1000
	s_waitcnt lgkmcnt(2)
	s_nop 0
	v_mfma_f32_16x16x32_bf16 v[122:125], v[166:169], v[154:157], v[122:125]
	v_mfma_f32_16x16x32_bf16 v[126:129], v[166:169], v[158:161], v[126:129]
	v_mfma_f32_16x16x32_bf16 v[118:121], v[166:169], v[162:165], v[118:121]
	v_mfma_f32_16x16x32_bf16 v[114:117], v[166:169], v[232:235], v[114:117]
	ds_read_b128 v[134:137], v177 offset:0x1800
	s_waitcnt lgkmcnt(2)
	s_nop 0
	v_mfma_f32_16x16x32_bf16 v[110:113], v[206:209], v[154:157], v[110:113]
	v_mfma_f32_16x16x32_bf16 v[106:109], v[206:209], v[158:161], v[106:109]
	v_mfma_f32_16x16x32_bf16 v[102:105], v[206:209], v[162:165], v[102:105]
	v_mfma_f32_16x16x32_bf16 v[98:101], v[206:209], v[232:235], v[98:101]
	ds_read_b128 v[138:141], v177 offset:0x2000
	ds_read_b128 v[236:239], v177 offset:0x2800
	s_waitcnt lgkmcnt(3)
	s_nop 0
	v_mfma_f32_16x16x32_bf16 v[94:97], v[130:133], v[154:157], v[94:97]
	v_mfma_f32_16x16x32_bf16 v[90:93], v[130:133], v[158:161], v[90:93]
	v_mfma_f32_16x16x32_bf16 v[86:89], v[130:133], v[162:165], v[86:89]
	v_mfma_f32_16x16x32_bf16 v[82:85], v[130:133], v[232:235], v[82:85]
	ds_read_b128 v[240:243], v177 offset:0x3000
	s_waitcnt lgkmcnt(3)
	s_nop 0
	v_mfma_f32_16x16x32_bf16 v[78:81], v[134:137], v[154:157], v[78:81]
	v_mfma_f32_16x16x32_bf16 v[74:77], v[134:137], v[158:161], v[74:77]
	v_mfma_f32_16x16x32_bf16 v[70:73], v[134:137], v[162:165], v[70:73]
	v_mfma_f32_16x16x32_bf16 v[66:69], v[134:137], v[232:235], v[66:69]
	ds_read_b128 v[244:247], v177 offset:0x3800
	s_waitcnt lgkmcnt(3)
	s_nop 0
	v_mfma_f32_16x16x32_bf16 v[62:65], v[138:141], v[154:157], v[62:65]
	v_mfma_f32_16x16x32_bf16 v[58:61], v[138:141], v[158:161], v[58:61]
	v_mfma_f32_16x16x32_bf16 v[54:57], v[138:141], v[162:165], v[54:57]
	v_mfma_f32_16x16x32_bf16 v[50:53], v[138:141], v[232:235], v[50:53]
	s_setprio 0
	s_waitcnt lgkmcnt(0)
	s_waitcnt vmcnt(0)
	s_add_i32 s19, s19, 0x10000
	s_addk_i32 s21, 0x80
	s_cmp_eq_u32 s21, 0x60800
	s_mov_b32 s2, 0x10000
	s_barrier
	s_cbranch_scc0 .Lrot2_top_l

.LBB0_273:
	s_add_i32 s18, s18, s24
	s_or_b32 s8, s20, s25
	s_cmpk_gt_i32 s8, 0x5ff
	s_waitcnt vmcnt(0)
	s_cselect_b64 s[10:11], -1, 0
	s_and_b64 s[20:21], s[44:45], s[10:11]
	v_or_b32_e32 v206, s18, v172
	s_mov_b64 s[10:11], -1
	s_andn2_b64 vcc, exec, s[20:21]
	v_lshlrev_b32_e32 v0, 2, v172
	s_cbranch_vccz .LBB0_277
	s_mov_b64 s[10:11], src_shared_base
	s_lshl_b32 s2, s24, 2
	s_add_i32 s10, s50, s2
	v_lshl_add_u64 v[130:131], s[10:11], 0, v[0:1]
	s_waitcnt vmcnt(0)
	ds_read_b128 v[166:169], v130
	ds_read_b128 v[162:165], v130 offset:64
	ds_read_b128 v[158:161], v130 offset:128
	ds_read_b128 v[154:157], v130 offset:192
	ds_read_b128 v[150:153], v130 offset:256
	ds_read_b128 v[146:149], v130 offset:320
	ds_read_b128 v[142:145], v130 offset:384
	ds_read_b128 v[138:141], v130 offset:448
	s_load_dword s2, s[78:79], 0x10
	s_load_dword s9, s[78:79], 0x0
	v_mov_b32_e32 v130, 0
	v_mov_b32_e32 v131, 0
	v_mov_b32_e32 v132, 0
	s_waitcnt lgkmcnt(0)
	s_lshr_b32 s2, s2, 16
	s_cmp_lg_u32 s2, 0
	s_cselect_b64 s[10:11], -1, 0
	s_cmp_lg_u64 s[10:11], 0
	s_addc_u32 s2, s9, s49
	s_cmp_ge_i32 s2, s23
	v_mov_b32_e32 v133, 0
	v_mov_b32_e32 v134, 0
	v_mov_b32_e32 v135, 0
	v_mov_b32_e32 v136, 0
	v_mov_b32_e32 v137, 0
	s_cbranch_scc1 .LBB0_276
	s_ashr_i32 s9, s2, 31
	s_lshr_b32 s9, s9, 29
	s_add_i32 s9, s2, s9
	s_ashr_i32 s10, s9, 3
	s_and_b32 s9, s9, -8
	s_sub_i32 s2, s2, s9
	s_cmp_lt_i32 s2, 0
	s_cselect_b32 s9, s48, s26
	s_mul_i32 s2, s9, s2
	s_add_i32 s2, s2, s10
	s_abs_i32 s10, s2
	s_mul_hi_u32 s11, s10, s28
	s_mul_i32 s19, s11, s27
	s_sub_i32 s10, s10, s19
	s_ashr_i32 s9, s2, 31
	s_add_i32 s19, s11, 1
	s_sub_i32 s20, s10, s27
	s_cmp_ge_u32 s10, s27
	s_cselect_b32 s11, s19, s11
	s_cselect_b32 s10, s20, s10
	s_add_i32 s19, s11, 1
	s_cmp_ge_u32 s10, s27
	s_cselect_b32 s10, s19, s11
	s_xor_b32 s10, s10, s9
	s_sub_i32 s9, s10, s9
	s_lshl_b32 s10, s9, 2
	s_sub_i32 s11, 64, s10
	s_min_i32 s11, s11, 4
	s_abs_i32 s19, s11
	v_cvt_f32_u32_e32 v130, s19
	s_sub_i32 s21, 0, s19
	s_mul_i32 s9, s9, s27
	s_sub_i32 s2, s2, s9
	v_rcp_iflag_f32_e32 v130, v130
	s_abs_i32 s20, s2
	s_xor_b32 s9, s2, s11
	s_ashr_i32 s9, s9, 31
	v_mul_f32_e32 v130, 0x4f7ffffe, v130
	v_cvt_u32_f32_e32 v130, v130
	s_mov_b32 m0, s29
	s_mov_b32 s54, s66
	s_mov_b32 s55, s67
	v_readfirstlane_b32 s51, v130
	s_mul_i32 s21, s21, s51
	s_mul_hi_u32 s21, s51, s21
	s_add_i32 s51, s51, s21
	s_mul_hi_u32 s21, s20, s51
	s_mul_i32 s51, s21, s19
	s_sub_i32 s20, s20, s51
	s_add_i32 s51, s21, 1
	s_sub_i32 s52, s20, s19
	s_cmp_ge_u32 s20, s19
	s_cselect_b32 s21, s51, s21
	s_cselect_b32 s20, s52, s20
	s_add_i32 s51, s21, 1
	s_cmp_ge_u32 s20, s19
	s_cselect_b32 s19, s51, s21
	s_xor_b32 s19, s19, s9
	s_sub_i32 s9, s19, s9
	s_mul_i32 s11, s9, s11
	s_sub_i32 s2, s2, s11
	s_add_i32 s2, s2, s10
	s_lshl_b32 s10, s2, 8
	s_ashr_i32 s11, s10, 31
	s_lshl_b32 s20, s9, 8
	v_add_u32_e32 v130, s10, v201
	s_lshl_b64 s[10:11], s[10:11], 11
	s_add_u32 s64, s94, s10
	s_addc_u32 s2, s95, s11
	s_ashr_i32 s21, s20, 31
	v_ashrrev_i32_e32 v131, 31, v130
	s_lshl_b64 s[10:11], s[20:21], 11
	v_lshlrev_b64 v[130:131], 6, v[130:131]
	s_add_u32 s52, s38, s10
	v_lshl_add_u64 v[134:135], v[174:175], 0, v[130:131]
	s_addc_u32 s9, s39, s11
	s_and_b32 s65, s2, 0xffff
	global_load_dwordx4 v[130:133], v[134:135], off offset:16
	s_nop 0
	global_load_dwordx4 v[134:137], v[134:135], off
	s_and_b32 s53, s9, 0xffff
	buffer_load_dwordx4 v173, s[64:67], 0 offen lds
	s_mov_b32 m0, s30
	s_nop 0
	buffer_load_dwordx4 v248, s[52:55], 0 offen lds
	s_mov_b32 m0, s31
	s_nop 0
	buffer_load_dwordx4 v173, s[64:67], s67 offen lds
	s_mov_b32 m0, s34
	s_nop 0
	buffer_load_dwordx4 v248, s[52:55], s67 offen lds
	s_mov_b32 m0, s35
	s_nop 0
	buffer_load_dwordx4 v173, s[64:67], s83 offen lds
	s_mov_b32 m0, s40
	s_nop 0
	buffer_load_dwordx4 v248, s[52:55], s83 offen lds
	s_mov_b32 m0, s41
	s_nop 0
	buffer_load_dwordx4 v173, s[64:67], s90 offen lds
	s_mov_b32 m0, s46
	s_nop 0
	buffer_load_dwordx4 v248, s[52:55], s90 offen lds
.LBB0_276:
	s_and_b32 s2, s15, 0xfffffe
	s_cmp_eq_u32 s2, 2
	s_cselect_b64 s[10:11], -1, 0
	s_and_b64 vcc, s[44:45], s[10:11]
	v_cndmask_b32_e32 v207, 1.0, v200, vcc
	v_mad_i64_i32 v[208:209], s[10:11], v206, s22, 0
	v_lshl_add_u64 v[208:209], v[208:209], 1, s[76:77]
	s_ashr_i32 s9, s8, 31
	v_lshl_add_u64 v[208:209], s[8:9], 1, v[208:209]
	v_mov_b32_e32 v177, v1
	s_nop 0
	s_lshl_b32 s62, s22, 1
	s_mov_b32 s15, s63
	v_lshl_add_u64 v[208:209], v[176:177], 2, v[208:209]
	v_mul_f32_e32 v254, v207, v166
	v_mul_f32_e32 v250, v122, v254
	v_mul_f32_e32 v251, v126, v254
	v_mul_f32_e32 v252, v118, v254
	v_mul_f32_e32 v253, v114, v254
	v_cvt_pk_bf16_f32 v250, v250, v251
	v_cvt_pk_bf16_f32 v251, v252, v253
	global_store_dwordx2 v[208:209], v[250:251], off
	v_lshl_add_u64 v[208:209], v[208:209], 0, s[62:63]
	v_mul_f32_e32 v254, v207, v167
	v_mul_f32_e32 v250, v123, v254
	v_mul_f32_e32 v251, v127, v254
	v_mul_f32_e32 v252, v119, v254
	v_mul_f32_e32 v253, v115, v254
	v_cvt_pk_bf16_f32 v250, v250, v251
	v_cvt_pk_bf16_f32 v251, v252, v253
	global_store_dwordx2 v[208:209], v[250:251], off
	v_lshl_add_u64 v[208:209], v[208:209], 0, s[62:63]
	v_mul_f32_e32 v254, v207, v168
	v_mul_f32_e32 v250, v124, v254
	v_mul_f32_e32 v251, v128, v254
	v_mul_f32_e32 v252, v120, v254
	v_mul_f32_e32 v253, v116, v254
	v_cvt_pk_bf16_f32 v250, v250, v251
	v_cvt_pk_bf16_f32 v251, v252, v253
	global_store_dwordx2 v[208:209], v[250:251], off
	v_lshl_add_u64 v[208:209], v[208:209], 0, s[62:63]
	v_mul_f32_e32 v254, v207, v169
	v_mul_f32_e32 v250, v125, v254
	v_mul_f32_e32 v251, v129, v254
	v_mul_f32_e32 v252, v121, v254
	v_mul_f32_e32 v253, v117, v254
	v_cvt_pk_bf16_f32 v250, v250, v251
	v_cvt_pk_bf16_f32 v251, v252, v253
	global_store_dwordx2 v[208:209], v[250:251], off
	v_lshl_add_u64 v[208:209], v[208:209], 0, s[62:63]
	v_lshl_add_u64 v[208:209], v[208:209], 0, s[14:15]
	v_mul_f32_e32 v254, v207, v162
	v_mul_f32_e32 v250, v110, v254
	v_mul_f32_e32 v251, v106, v254
	v_mul_f32_e32 v252, v102, v254
	v_mul_f32_e32 v253, v98, v254
	v_cvt_pk_bf16_f32 v250, v250, v251
	v_cvt_pk_bf16_f32 v251, v252, v253
	global_store_dwordx2 v[208:209], v[250:251], off
	v_lshl_add_u64 v[208:209], v[208:209], 0, s[62:63]
	v_mul_f32_e32 v254, v207, v163
	v_mul_f32_e32 v250, v111, v254
	v_mul_f32_e32 v251, v107, v254
	v_mul_f32_e32 v252, v103, v254
	v_mul_f32_e32 v253, v99, v254
	v_cvt_pk_bf16_f32 v250, v250, v251
	v_cvt_pk_bf16_f32 v251, v252, v253
	global_store_dwordx2 v[208:209], v[250:251], off
	v_lshl_add_u64 v[208:209], v[208:209], 0, s[62:63]
	v_mul_f32_e32 v254, v207, v164
	v_mul_f32_e32 v250, v112, v254
	v_mul_f32_e32 v251, v108, v254
	v_mul_f32_e32 v252, v104, v254
	v_mul_f32_e32 v253, v100, v254
	v_cvt_pk_bf16_f32 v250, v250, v251
	v_cvt_pk_bf16_f32 v251, v252, v253
	global_store_dwordx2 v[208:209], v[250:251], off
	v_lshl_add_u64 v[208:209], v[208:209], 0, s[62:63]
	v_mul_f32_e32 v254, v207, v165
	v_mul_f32_e32 v250, v113, v254
	v_mul_f32_e32 v251, v109, v254
	v_mul_f32_e32 v252, v105, v254
	v_mul_f32_e32 v253, v101, v254
	v_cvt_pk_bf16_f32 v250, v250, v251
	v_cvt_pk_bf16_f32 v251, v252, v253
	global_store_dwordx2 v[208:209], v[250:251], off
	v_lshl_add_u64 v[208:209], v[208:209], 0, s[62:63]
	v_lshl_add_u64 v[208:209], v[208:209], 0, s[14:15]
	v_mul_f32_e32 v254, v207, v158
	v_mul_f32_e32 v250, v94, v254
	v_mul_f32_e32 v251, v90, v254
	v_mul_f32_e32 v252, v86, v254
	v_mul_f32_e32 v253, v82, v254
	v_cvt_pk_bf16_f32 v250, v250, v251
	v_cvt_pk_bf16_f32 v251, v252, v253
	global_store_dwordx2 v[208:209], v[250:251], off
	v_lshl_add_u64 v[208:209], v[208:209], 0, s[62:63]
	v_mul_f32_e32 v254, v207, v159
	v_mul_f32_e32 v250, v95, v254
	v_mul_f32_e32 v251, v91, v254
	v_mul_f32_e32 v252, v87, v254
	v_mul_f32_e32 v253, v83, v254
	v_cvt_pk_bf16_f32 v250, v250, v251
	v_cvt_pk_bf16_f32 v251, v252, v253
	global_store_dwordx2 v[208:209], v[250:251], off
	v_lshl_add_u64 v[208:209], v[208:209], 0, s[62:63]
	v_mul_f32_e32 v254, v207, v160
	v_mul_f32_e32 v250, v96, v254
	v_mul_f32_e32 v251, v92, v254
	v_mul_f32_e32 v252, v88, v254
	v_mul_f32_e32 v253, v84, v254
	v_cvt_pk_bf16_f32 v250, v250, v251
	v_cvt_pk_bf16_f32 v251, v252, v253
	global_store_dwordx2 v[208:209], v[250:251], off
	v_lshl_add_u64 v[208:209], v[208:209], 0, s[62:63]
	v_mul_f32_e32 v254, v207, v161
	v_mul_f32_e32 v250, v97, v254
	v_mul_f32_e32 v251, v93, v254
	v_mul_f32_e32 v252, v89, v254
	v_mul_f32_e32 v253, v85, v254
	v_cvt_pk_bf16_f32 v250, v250, v251
	v_cvt_pk_bf16_f32 v251, v252, v253
	global_store_dwordx2 v[208:209], v[250:251], off
	v_lshl_add_u64 v[208:209], v[208:209], 0, s[62:63]
	v_lshl_add_u64 v[208:209], v[208:209], 0, s[14:15]
	v_mul_f32_e32 v254, v207, v154
	v_mul_f32_e32 v250, v78, v254
	v_mul_f32_e32 v251, v74, v254
	v_mul_f32_e32 v252, v70, v254
	v_mul_f32_e32 v253, v66, v254
	v_cvt_pk_bf16_f32 v250, v250, v251
	v_cvt_pk_bf16_f32 v251, v252, v253
	global_store_dwordx2 v[208:209], v[250:251], off
	v_lshl_add_u64 v[208:209], v[208:209], 0, s[62:63]
	v_mul_f32_e32 v254, v207, v155
	v_mul_f32_e32 v250, v79, v254
	v_mul_f32_e32 v251, v75, v254
	v_mul_f32_e32 v252, v71, v254
	v_mul_f32_e32 v253, v67, v254
	v_cvt_pk_bf16_f32 v250, v250, v251
	v_cvt_pk_bf16_f32 v251, v252, v253
	global_store_dwordx2 v[208:209], v[250:251], off
	v_lshl_add_u64 v[208:209], v[208:209], 0, s[62:63]
	v_mul_f32_e32 v254, v207, v156
	v_mul_f32_e32 v250, v80, v254
	v_mul_f32_e32 v251, v76, v254
	v_mul_f32_e32 v252, v72, v254
	v_mul_f32_e32 v253, v68, v254
	v_cvt_pk_bf16_f32 v250, v250, v251
	v_cvt_pk_bf16_f32 v251, v252, v253
	global_store_dwordx2 v[208:209], v[250:251], off
	v_lshl_add_u64 v[208:209], v[208:209], 0, s[62:63]
	v_mul_f32_e32 v254, v207, v157
	v_mul_f32_e32 v250, v81, v254
	v_mul_f32_e32 v251, v77, v254
	v_mul_f32_e32 v252, v73, v254
	v_mul_f32_e32 v253, v69, v254
	v_cvt_pk_bf16_f32 v250, v250, v251
	v_cvt_pk_bf16_f32 v251, v252, v253
	global_store_dwordx2 v[208:209], v[250:251], off
	v_lshl_add_u64 v[208:209], v[208:209], 0, s[62:63]
	v_lshl_add_u64 v[208:209], v[208:209], 0, s[14:15]
	v_mul_f32_e32 v254, v207, v150
	v_mul_f32_e32 v250, v62, v254
	v_mul_f32_e32 v251, v58, v254
	v_mul_f32_e32 v252, v54, v254
	v_mul_f32_e32 v253, v50, v254
	v_cvt_pk_bf16_f32 v250, v250, v251
	v_cvt_pk_bf16_f32 v251, v252, v253
	global_store_dwordx2 v[208:209], v[250:251], off
	v_lshl_add_u64 v[208:209], v[208:209], 0, s[62:63]
	v_mul_f32_e32 v254, v207, v151
	v_mul_f32_e32 v250, v63, v254
	v_mul_f32_e32 v251, v59, v254
	v_mul_f32_e32 v252, v55, v254
	v_mul_f32_e32 v253, v51, v254
	v_cvt_pk_bf16_f32 v250, v250, v251
	v_cvt_pk_bf16_f32 v251, v252, v253
	global_store_dwordx2 v[208:209], v[250:251], off
	v_lshl_add_u64 v[208:209], v[208:209], 0, s[62:63]
	v_mul_f32_e32 v254, v207, v152
	v_mul_f32_e32 v250, v64, v254
	v_mul_f32_e32 v251, v60, v254
	v_mul_f32_e32 v252, v56, v254
	v_mul_f32_e32 v253, v52, v254
	v_cvt_pk_bf16_f32 v250, v250, v251
	v_cvt_pk_bf16_f32 v251, v252, v253
	global_store_dwordx2 v[208:209], v[250:251], off
	v_lshl_add_u64 v[208:209], v[208:209], 0, s[62:63]
	v_mul_f32_e32 v254, v207, v153
	v_mul_f32_e32 v250, v65, v254
	v_mul_f32_e32 v251, v61, v254
	v_mul_f32_e32 v252, v57, v254
	v_mul_f32_e32 v253, v53, v254
	v_cvt_pk_bf16_f32 v250, v250, v251
	v_cvt_pk_bf16_f32 v251, v252, v253
	global_store_dwordx2 v[208:209], v[250:251], off
	v_lshl_add_u64 v[208:209], v[208:209], 0, s[62:63]
	v_lshl_add_u64 v[208:209], v[208:209], 0, s[14:15]
	v_mul_f32_e32 v254, v207, v146
	v_mul_f32_e32 v250, v46, v254
	v_mul_f32_e32 v251, v42, v254
	v_mul_f32_e32 v252, v38, v254
	v_mul_f32_e32 v253, v34, v254
	v_cvt_pk_bf16_f32 v250, v250, v251
	v_cvt_pk_bf16_f32 v251, v252, v253
	global_store_dwordx2 v[208:209], v[250:251], off
	v_lshl_add_u64 v[208:209], v[208:209], 0, s[62:63]
	v_mul_f32_e32 v254, v207, v147
	v_mul_f32_e32 v250, v47, v254
	v_mul_f32_e32 v251, v43, v254
	v_mul_f32_e32 v252, v39, v254
	v_mul_f32_e32 v253, v35, v254
	v_cvt_pk_bf16_f32 v250, v250, v251
	v_cvt_pk_bf16_f32 v251, v252, v253
	global_store_dwordx2 v[208:209], v[250:251], off
	v_lshl_add_u64 v[208:209], v[208:209], 0, s[62:63]
	v_mul_f32_e32 v254, v207, v148
	v_mul_f32_e32 v250, v48, v254
	v_mul_f32_e32 v251, v44, v254
	v_mul_f32_e32 v252, v40, v254
	v_mul_f32_e32 v253, v36, v254
	v_cvt_pk_bf16_f32 v250, v250, v251
	v_cvt_pk_bf16_f32 v251, v252, v253
	global_store_dwordx2 v[208:209], v[250:251], off
	v_lshl_add_u64 v[208:209], v[208:209], 0, s[62:63]
	v_mul_f32_e32 v254, v207, v149
	v_mul_f32_e32 v250, v49, v254
	v_mul_f32_e32 v251, v45, v254
	v_mul_f32_e32 v252, v41, v254
	v_mul_f32_e32 v253, v37, v254
	v_cvt_pk_bf16_f32 v250, v250, v251
	v_cvt_pk_bf16_f32 v251, v252, v253
	global_store_dwordx2 v[208:209], v[250:251], off
	v_lshl_add_u64 v[208:209], v[208:209], 0, s[62:63]
	v_lshl_add_u64 v[208:209], v[208:209], 0, s[14:15]
	v_mul_f32_e32 v254, v207, v142
	v_mul_f32_e32 v250, v30, v254
	v_mul_f32_e32 v251, v26, v254
	v_mul_f32_e32 v252, v22, v254
	v_mul_f32_e32 v253, v18, v254
	v_cvt_pk_bf16_f32 v250, v250, v251
	v_cvt_pk_bf16_f32 v251, v252, v253
	global_store_dwordx2 v[208:209], v[250:251], off
	v_lshl_add_u64 v[208:209], v[208:209], 0, s[62:63]
	v_mul_f32_e32 v254, v207, v143
	v_mul_f32_e32 v250, v31, v254
	v_mul_f32_e32 v251, v27, v254
	v_mul_f32_e32 v252, v23, v254
	v_mul_f32_e32 v253, v19, v254
	v_cvt_pk_bf16_f32 v250, v250, v251
	v_cvt_pk_bf16_f32 v251, v252, v253
	global_store_dwordx2 v[208:209], v[250:251], off
	v_lshl_add_u64 v[208:209], v[208:209], 0, s[62:63]
	v_mul_f32_e32 v254, v207, v144
	v_mul_f32_e32 v250, v32, v254
	v_mul_f32_e32 v251, v28, v254
	v_mul_f32_e32 v252, v24, v254
	v_mul_f32_e32 v253, v20, v254
	v_cvt_pk_bf16_f32 v250, v250, v251
	v_cvt_pk_bf16_f32 v251, v252, v253
	global_store_dwordx2 v[208:209], v[250:251], off
	v_lshl_add_u64 v[208:209], v[208:209], 0, s[62:63]
	v_mul_f32_e32 v254, v207, v145
	v_mul_f32_e32 v250, v33, v254
	v_mul_f32_e32 v251, v29, v254
	v_mul_f32_e32 v252, v25, v254
	v_mul_f32_e32 v253, v21, v254
	v_cvt_pk_bf16_f32 v250, v250, v251
	v_cvt_pk_bf16_f32 v251, v252, v253
	global_store_dwordx2 v[208:209], v[250:251], off
	v_lshl_add_u64 v[208:209], v[208:209], 0, s[62:63]
	v_lshl_add_u64 v[208:209], v[208:209], 0, s[14:15]
	v_mul_f32_e32 v254, v207, v138
	v_mul_f32_e32 v250, v14, v254
	v_mul_f32_e32 v251, v10, v254
	v_mul_f32_e32 v252, v6, v254
	v_mul_f32_e32 v253, v2, v254
	v_cvt_pk_bf16_f32 v250, v250, v251
	v_cvt_pk_bf16_f32 v251, v252, v253
	global_store_dwordx2 v[208:209], v[250:251], off
	v_lshl_add_u64 v[208:209], v[208:209], 0, s[62:63]
	v_mul_f32_e32 v254, v207, v139
	v_mul_f32_e32 v250, v15, v254
	v_mul_f32_e32 v251, v11, v254
	v_mul_f32_e32 v252, v7, v254
	v_mul_f32_e32 v253, v3, v254
	v_cvt_pk_bf16_f32 v250, v250, v251
	v_cvt_pk_bf16_f32 v251, v252, v253
	global_store_dwordx2 v[208:209], v[250:251], off
	v_lshl_add_u64 v[208:209], v[208:209], 0, s[62:63]
	v_mul_f32_e32 v254, v207, v140
	v_mul_f32_e32 v250, v16, v254
	v_mul_f32_e32 v251, v12, v254
	v_mul_f32_e32 v252, v8, v254
	v_mul_f32_e32 v253, v4, v254
	v_cvt_pk_bf16_f32 v250, v250, v251
	v_cvt_pk_bf16_f32 v251, v252, v253
	global_store_dwordx2 v[208:209], v[250:251], off
	v_lshl_add_u64 v[208:209], v[208:209], 0, s[62:63]
	v_mul_f32_e32 v254, v207, v141
	v_mul_f32_e32 v250, v17, v254
	v_mul_f32_e32 v251, v13, v254
	v_mul_f32_e32 v252, v9, v254
	v_mul_f32_e32 v253, v5, v254
	v_cvt_pk_bf16_f32 v250, v250, v251
	v_cvt_pk_bf16_f32 v251, v252, v253
	global_store_dwordx2 v[208:209], v[250:251], off
	v_lshl_add_u64 v[208:209], v[208:209], 0, s[62:63]
	v_lshl_add_u64 v[208:209], v[208:209], 0, s[14:15]
	s_mov_b64 s[10:11], 0
.LBB0_277:
	s_and_b64 vcc, exec, s[10:11]
	s_cbranch_vccz .LBB0_281
	s_lshl_b32 s2, s24, 2
	s_mov_b64 s[20:21], src_shared_base
	s_add_i32 s10, s50, s2
	s_mov_b32 s11, s21
	v_lshl_add_u64 v[130:131], s[10:11], 0, v[0:1]
	s_waitcnt vmcnt(0)
	ds_read_b128 v[166:169], v130
	ds_read_b128 v[162:165], v130 offset:64
	ds_read_b128 v[158:161], v130 offset:128
	ds_read_b128 v[154:157], v130 offset:192
	ds_read_b128 v[150:153], v130 offset:256
	ds_read_b128 v[146:149], v130 offset:320
	ds_read_b128 v[142:145], v130 offset:384
	ds_read_b128 v[138:141], v130 offset:448
	s_load_dword s2, s[78:79], 0x10
	s_load_dword s9, s[78:79], 0x0
	v_mov_b32_e32 v130, 0
	v_mov_b32_e32 v131, 0
	v_mov_b32_e32 v132, 0
	s_waitcnt lgkmcnt(0)
	s_lshr_b32 s2, s2, 16
	s_cmp_lg_u32 s2, 0
	s_cselect_b64 s[10:11], -1, 0
	s_cmp_lg_u64 s[10:11], 0
	s_addc_u32 s2, s9, s49
	s_cmp_ge_i32 s2, s23
	v_mov_b32_e32 v133, 0
	v_mov_b32_e32 v134, 0
	v_mov_b32_e32 v135, 0
	v_mov_b32_e32 v136, 0
	v_mov_b32_e32 v137, 0
	s_cbranch_scc1 .LBB0_280
	s_ashr_i32 s9, s2, 31
	s_lshr_b32 s9, s9, 29
	s_add_i32 s9, s2, s9
	s_ashr_i32 s10, s9, 3
	s_and_b32 s9, s9, -8
	s_sub_i32 s2, s2, s9
	s_cmp_lt_i32 s2, 0
	s_cselect_b32 s9, s48, s26
	s_mul_i32 s2, s9, s2
	s_add_i32 s2, s2, s10
	s_abs_i32 s10, s2
	s_mul_hi_u32 s11, s10, s28
	s_mul_i32 s15, s11, s27
	s_sub_i32 s10, s10, s15
	s_ashr_i32 s9, s2, 31
	s_add_i32 s15, s11, 1
	s_sub_i32 s19, s10, s27
	s_cmp_ge_u32 s10, s27
	s_cselect_b32 s11, s15, s11
	s_cselect_b32 s10, s19, s10
	s_add_i32 s15, s11, 1
	s_cmp_ge_u32 s10, s27
	s_cselect_b32 s10, s15, s11
	s_xor_b32 s10, s10, s9
	s_sub_i32 s9, s10, s9
	s_lshl_b32 s10, s9, 2
	s_sub_i32 s11, 64, s10
	s_min_i32 s11, s11, 4
	s_abs_i32 s15, s11
	v_cvt_f32_u32_e32 v0, s15
	s_sub_i32 s20, 0, s15
	s_mul_i32 s9, s9, s27
	s_sub_i32 s2, s2, s9
	v_rcp_iflag_f32_e32 v0, v0
	s_abs_i32 s19, s2
	s_xor_b32 s9, s2, s11
	s_ashr_i32 s9, s9, 31
	v_mul_f32_e32 v0, 0x4f7ffffe, v0
	v_cvt_u32_f32_e32 v0, v0
	s_mov_b32 m0, s29
	s_mov_b32 s54, s66
	s_mov_b32 s55, s67
	v_readfirstlane_b32 s21, v0
	s_mul_i32 s20, s20, s21
	s_mul_hi_u32 s20, s21, s20
	s_add_i32 s21, s21, s20
	s_mul_hi_u32 s20, s19, s21
	s_mul_i32 s21, s20, s15
	s_sub_i32 s19, s19, s21
	s_add_i32 s21, s20, 1
	s_sub_i32 s50, s19, s15
	s_cmp_ge_u32 s19, s15
	s_cselect_b32 s20, s21, s20
	s_cselect_b32 s19, s50, s19
	s_add_i32 s21, s20, 1
	s_cmp_ge_u32 s19, s15
	s_cselect_b32 s15, s21, s20
	s_xor_b32 s15, s15, s9
	s_sub_i32 s9, s15, s9
	s_mul_i32 s11, s9, s11
	s_sub_i32 s2, s2, s11
	s_add_i32 s2, s2, s10
	s_lshl_b32 s10, s2, 8
	s_ashr_i32 s11, s10, 31
	s_lshl_b32 s20, s9, 8
	v_add_u32_e32 v130, s10, v201
	s_lshl_b64 s[10:11], s[10:11], 11
	s_add_u32 s64, s94, s10
	s_addc_u32 s2, s95, s11
	s_ashr_i32 s21, s20, 31
	v_ashrrev_i32_e32 v131, 31, v130
	s_lshl_b64 s[10:11], s[20:21], 11
	v_lshlrev_b64 v[130:131], 6, v[130:131]
	s_add_u32 s52, s38, s10
	v_lshl_add_u64 v[134:135], v[174:175], 0, v[130:131]
	s_addc_u32 s9, s39, s11
	s_and_b32 s65, s2, 0xffff
	global_load_dwordx4 v[130:133], v[134:135], off offset:16
	s_nop 0
	global_load_dwordx4 v[134:137], v[134:135], off
	s_and_b32 s53, s9, 0xffff
	buffer_load_dwordx4 v173, s[64:67], 0 offen lds
	s_mov_b32 m0, s30
	s_nop 0
	buffer_load_dwordx4 v248, s[52:55], 0 offen lds
	s_mov_b32 m0, s31
	s_nop 0
	buffer_load_dwordx4 v173, s[64:67], s67 offen lds
	s_mov_b32 m0, s34
	s_nop 0
	buffer_load_dwordx4 v248, s[52:55], s67 offen lds
	s_mov_b32 m0, s35
	s_nop 0
	buffer_load_dwordx4 v173, s[64:67], s83 offen lds
	s_mov_b32 m0, s40
	s_nop 0
	buffer_load_dwordx4 v248, s[52:55], s83 offen lds
	s_mov_b32 m0, s41
	s_nop 0
	buffer_load_dwordx4 v173, s[64:67], s90 offen lds
	s_mov_b32 m0, s46
	s_nop 0
	buffer_load_dwordx4 v248, s[52:55], s90 offen lds
.LBB0_280:
	s_ashr_i32 s2, s18, 3
	s_and_b32 s2, s2, 0xfffffe00
	s_add_i32 s2, s2, s8
	v_and_b32_e32 v0, 0xf8c, v206
	v_add_u32_e32 v206, s2, v203
	v_ashrrev_i32_e32 v207, 31, v206
	v_lshlrev_b64 v[206:207], 13, v[206:207]
	v_lshl_add_u64 v[206:207], s[36:37], 0, v[206:207]
	v_lshlrev_b32_e32 v0, 1, v0
	v_lshl_add_u64 v[206:207], v[206:207], 0, v[0:1]
	s_nop 0
	v_mul_u32_u24_e32 v254, 0x3000, v176
	v_mov_b32_e32 v255, 0
	v_lshl_add_u64 v[206:207], v[254:255], 0, v[206:207]
	s_movk_i32 s62, 0x2000
	v_mul_f32_e32 v250, v122, v166
	v_mul_f32_e32 v251, v123, v167
	v_mul_f32_e32 v252, v124, v168
	v_mul_f32_e32 v253, v125, v169
	v_cvt_pk_bf16_f32 v250, v250, v251
	v_cvt_pk_bf16_f32 v251, v252, v253
	global_store_dwordx2 v[206:207], v[250:251], off offset:0
	v_mul_f32_e32 v250, v110, v162
	v_mul_f32_e32 v251, v111, v163
	v_mul_f32_e32 v252, v112, v164
	v_mul_f32_e32 v253, v113, v165
	v_cvt_pk_bf16_f32 v250, v250, v251
	v_cvt_pk_bf16_f32 v251, v252, v253
	global_store_dwordx2 v[206:207], v[250:251], off offset:32
	v_mul_f32_e32 v250, v94, v158
	v_mul_f32_e32 v251, v95, v159
	v_mul_f32_e32 v252, v96, v160
	v_mul_f32_e32 v253, v97, v161
	v_cvt_pk_bf16_f32 v250, v250, v251
	v_cvt_pk_bf16_f32 v251, v252, v253
	global_store_dwordx2 v[206:207], v[250:251], off offset:64
	v_mul_f32_e32 v250, v78, v154
	v_mul_f32_e32 v251, v79, v155
	v_mul_f32_e32 v252, v80, v156
	v_mul_f32_e32 v253, v81, v157
	v_cvt_pk_bf16_f32 v250, v250, v251
	v_cvt_pk_bf16_f32 v251, v252, v253
	global_store_dwordx2 v[206:207], v[250:251], off offset:96
	v_mul_f32_e32 v250, v62, v150
	v_mul_f32_e32 v251, v63, v151
	v_mul_f32_e32 v252, v64, v152
	v_mul_f32_e32 v253, v65, v153
	v_cvt_pk_bf16_f32 v250, v250, v251
	v_cvt_pk_bf16_f32 v251, v252, v253
	global_store_dwordx2 v[206:207], v[250:251], off offset:128
	v_mul_f32_e32 v250, v46, v146
	v_mul_f32_e32 v251, v47, v147
	v_mul_f32_e32 v252, v48, v148
	v_mul_f32_e32 v253, v49, v149
	v_cvt_pk_bf16_f32 v250, v250, v251
	v_cvt_pk_bf16_f32 v251, v252, v253
	global_store_dwordx2 v[206:207], v[250:251], off offset:160
	v_mul_f32_e32 v250, v30, v142
	v_mul_f32_e32 v251, v31, v143
	v_mul_f32_e32 v252, v32, v144
	v_mul_f32_e32 v253, v33, v145
	v_cvt_pk_bf16_f32 v250, v250, v251
	v_cvt_pk_bf16_f32 v251, v252, v253
	global_store_dwordx2 v[206:207], v[250:251], off offset:192
	v_mul_f32_e32 v250, v14, v138
	v_mul_f32_e32 v251, v15, v139
	v_mul_f32_e32 v252, v16, v140
	v_mul_f32_e32 v253, v17, v141
	v_cvt_pk_bf16_f32 v250, v250, v251
	v_cvt_pk_bf16_f32 v251, v252, v253
	global_store_dwordx2 v[206:207], v[250:251], off offset:224
	v_lshl_add_u64 v[206:207], v[206:207], 0, s[62:63]
	v_mul_f32_e32 v250, v126, v166
	v_mul_f32_e32 v251, v127, v167
	v_mul_f32_e32 v252, v128, v168
	v_mul_f32_e32 v253, v129, v169
	v_cvt_pk_bf16_f32 v250, v250, v251
	v_cvt_pk_bf16_f32 v251, v252, v253
	global_store_dwordx2 v[206:207], v[250:251], off offset:0
	v_mul_f32_e32 v250, v106, v162
	v_mul_f32_e32 v251, v107, v163
	v_mul_f32_e32 v252, v108, v164
	v_mul_f32_e32 v253, v109, v165
	v_cvt_pk_bf16_f32 v250, v250, v251
	v_cvt_pk_bf16_f32 v251, v252, v253
	global_store_dwordx2 v[206:207], v[250:251], off offset:32
	v_mul_f32_e32 v250, v90, v158
	v_mul_f32_e32 v251, v91, v159
	v_mul_f32_e32 v252, v92, v160
	v_mul_f32_e32 v253, v93, v161
	v_cvt_pk_bf16_f32 v250, v250, v251
	v_cvt_pk_bf16_f32 v251, v252, v253
	global_store_dwordx2 v[206:207], v[250:251], off offset:64
	v_mul_f32_e32 v250, v74, v154
	v_mul_f32_e32 v251, v75, v155
	v_mul_f32_e32 v252, v76, v156
	v_mul_f32_e32 v253, v77, v157
	v_cvt_pk_bf16_f32 v250, v250, v251
	v_cvt_pk_bf16_f32 v251, v252, v253
	global_store_dwordx2 v[206:207], v[250:251], off offset:96
	v_mul_f32_e32 v250, v58, v150
	v_mul_f32_e32 v251, v59, v151
	v_mul_f32_e32 v252, v60, v152
	v_mul_f32_e32 v253, v61, v153
	v_cvt_pk_bf16_f32 v250, v250, v251
	v_cvt_pk_bf16_f32 v251, v252, v253
	global_store_dwordx2 v[206:207], v[250:251], off offset:128
	v_mul_f32_e32 v250, v42, v146
	v_mul_f32_e32 v251, v43, v147
	v_mul_f32_e32 v252, v44, v148
	v_mul_f32_e32 v253, v45, v149
	v_cvt_pk_bf16_f32 v250, v250, v251
	v_cvt_pk_bf16_f32 v251, v252, v253
	global_store_dwordx2 v[206:207], v[250:251], off offset:160
	v_mul_f32_e32 v250, v26, v142
	v_mul_f32_e32 v251, v27, v143
	v_mul_f32_e32 v252, v28, v144
	v_mul_f32_e32 v253, v29, v145
	v_cvt_pk_bf16_f32 v250, v250, v251
	v_cvt_pk_bf16_f32 v251, v252, v253
	global_store_dwordx2 v[206:207], v[250:251], off offset:192
	v_mul_f32_e32 v250, v10, v138
	v_mul_f32_e32 v251, v11, v139
	v_mul_f32_e32 v252, v12, v140
	v_mul_f32_e32 v253, v13, v141
	v_cvt_pk_bf16_f32 v250, v250, v251
	v_cvt_pk_bf16_f32 v251, v252, v253
	global_store_dwordx2 v[206:207], v[250:251], off offset:224
	v_lshl_add_u64 v[206:207], v[206:207], 0, s[62:63]
	v_mul_f32_e32 v250, v118, v166
	v_mul_f32_e32 v251, v119, v167
	v_mul_f32_e32 v252, v120, v168
	v_mul_f32_e32 v253, v121, v169
	v_cvt_pk_bf16_f32 v250, v250, v251
	v_cvt_pk_bf16_f32 v251, v252, v253
	global_store_dwordx2 v[206:207], v[250:251], off offset:0
	v_mul_f32_e32 v250, v102, v162
	v_mul_f32_e32 v251, v103, v163
	v_mul_f32_e32 v252, v104, v164
	v_mul_f32_e32 v253, v105, v165
	v_cvt_pk_bf16_f32 v250, v250, v251
	v_cvt_pk_bf16_f32 v251, v252, v253
	global_store_dwordx2 v[206:207], v[250:251], off offset:32
	v_mul_f32_e32 v250, v86, v158
	v_mul_f32_e32 v251, v87, v159
	v_mul_f32_e32 v252, v88, v160
	v_mul_f32_e32 v253, v89, v161
	v_cvt_pk_bf16_f32 v250, v250, v251
	v_cvt_pk_bf16_f32 v251, v252, v253
	global_store_dwordx2 v[206:207], v[250:251], off offset:64
	v_mul_f32_e32 v250, v70, v154
	v_mul_f32_e32 v251, v71, v155
	v_mul_f32_e32 v252, v72, v156
	v_mul_f32_e32 v253, v73, v157
	v_cvt_pk_bf16_f32 v250, v250, v251
	v_cvt_pk_bf16_f32 v251, v252, v253
	global_store_dwordx2 v[206:207], v[250:251], off offset:96
	v_mul_f32_e32 v250, v54, v150
	v_mul_f32_e32 v251, v55, v151
	v_mul_f32_e32 v252, v56, v152
	v_mul_f32_e32 v253, v57, v153
	v_cvt_pk_bf16_f32 v250, v250, v251
	v_cvt_pk_bf16_f32 v251, v252, v253
	global_store_dwordx2 v[206:207], v[250:251], off offset:128
	v_mul_f32_e32 v250, v38, v146
	v_mul_f32_e32 v251, v39, v147
	v_mul_f32_e32 v252, v40, v148
	v_mul_f32_e32 v253, v41, v149
	v_cvt_pk_bf16_f32 v250, v250, v251
	v_cvt_pk_bf16_f32 v251, v252, v253
	global_store_dwordx2 v[206:207], v[250:251], off offset:160
	v_mul_f32_e32 v250, v22, v142
	v_mul_f32_e32 v251, v23, v143
	v_mul_f32_e32 v252, v24, v144
	v_mul_f32_e32 v253, v25, v145
	v_cvt_pk_bf16_f32 v250, v250, v251
	v_cvt_pk_bf16_f32 v251, v252, v253
	global_store_dwordx2 v[206:207], v[250:251], off offset:192
	v_mul_f32_e32 v250, v6, v138
	v_mul_f32_e32 v251, v7, v139
	v_mul_f32_e32 v252, v8, v140
	v_mul_f32_e32 v253, v9, v141
	v_cvt_pk_bf16_f32 v250, v250, v251
	v_cvt_pk_bf16_f32 v251, v252, v253
	global_store_dwordx2 v[206:207], v[250:251], off offset:224
	v_lshl_add_u64 v[206:207], v[206:207], 0, s[62:63]
	v_mul_f32_e32 v250, v114, v166
	v_mul_f32_e32 v251, v115, v167
	v_mul_f32_e32 v252, v116, v168
	v_mul_f32_e32 v253, v117, v169
	v_cvt_pk_bf16_f32 v250, v250, v251
	v_cvt_pk_bf16_f32 v251, v252, v253
	global_store_dwordx2 v[206:207], v[250:251], off offset:0
	v_mul_f32_e32 v250, v98, v162
	v_mul_f32_e32 v251, v99, v163
	v_mul_f32_e32 v252, v100, v164
	v_mul_f32_e32 v253, v101, v165
	v_cvt_pk_bf16_f32 v250, v250, v251
	v_cvt_pk_bf16_f32 v251, v252, v253
	global_store_dwordx2 v[206:207], v[250:251], off offset:32
	v_mul_f32_e32 v250, v82, v158
	v_mul_f32_e32 v251, v83, v159
	v_mul_f32_e32 v252, v84, v160
	v_mul_f32_e32 v253, v85, v161
	v_cvt_pk_bf16_f32 v250, v250, v251
	v_cvt_pk_bf16_f32 v251, v252, v253
	global_store_dwordx2 v[206:207], v[250:251], off offset:64
	v_mul_f32_e32 v250, v66, v154
	v_mul_f32_e32 v251, v67, v155
	v_mul_f32_e32 v252, v68, v156
	v_mul_f32_e32 v253, v69, v157
	v_cvt_pk_bf16_f32 v250, v250, v251
	v_cvt_pk_bf16_f32 v251, v252, v253
	global_store_dwordx2 v[206:207], v[250:251], off offset:96
	v_mul_f32_e32 v250, v50, v150
	v_mul_f32_e32 v251, v51, v151
	v_mul_f32_e32 v252, v52, v152
	v_mul_f32_e32 v253, v53, v153
	v_cvt_pk_bf16_f32 v250, v250, v251
	v_cvt_pk_bf16_f32 v251, v252, v253
	global_store_dwordx2 v[206:207], v[250:251], off offset:128
	v_mul_f32_e32 v250, v34, v146
	v_mul_f32_e32 v251, v35, v147
	v_mul_f32_e32 v252, v36, v148
	v_mul_f32_e32 v253, v37, v149
	v_cvt_pk_bf16_f32 v250, v250, v251
	v_cvt_pk_bf16_f32 v251, v252, v253
	global_store_dwordx2 v[206:207], v[250:251], off offset:160
	v_mul_f32_e32 v250, v18, v142
	v_mul_f32_e32 v251, v19, v143
	v_mul_f32_e32 v252, v20, v144
	v_mul_f32_e32 v253, v21, v145
	v_cvt_pk_bf16_f32 v250, v250, v251
	v_cvt_pk_bf16_f32 v251, v252, v253
	global_store_dwordx2 v[206:207], v[250:251], off offset:192
	v_mul_f32_e32 v250, v2, v138
	v_mul_f32_e32 v251, v3, v139
	v_mul_f32_e32 v252, v4, v140
	v_mul_f32_e32 v253, v5, v141
	v_cvt_pk_bf16_f32 v250, v250, v251
	v_cvt_pk_bf16_f32 v251, v252, v253
	global_store_dwordx2 v[206:207], v[250:251], off offset:224

.LBB0_431:
	s_lshl_b32 s2, s20, 2
	s_add_i32 s68, s34, s2
	v_lshl_add_u64 v[50:51], s[68:69], 0, v[0:1]
	s_waitcnt vmcnt(0)
	s_waitcnt vmcnt(0)
	ds_read_b128 v[166:169], v50
	ds_read_b128 v[162:165], v50 offset:64
	ds_read_b128 v[158:161], v50 offset:128
	ds_read_b128 v[138:141], v50 offset:192
	ds_read_b128 v[118:121], v50 offset:256
	ds_read_b128 v[98:101], v50 offset:320
	ds_read_b128 v[78:81], v50 offset:384
	ds_read_b128 v[58:61], v50 offset:448
	s_load_dword s2, s[78:79], 0x0
	v_mov_b32_e32 v50, 0
	v_mov_b32_e32 v51, 0
	v_mov_b32_e32 v52, 0
	v_mov_b32_e32 v53, 0
	s_waitcnt lgkmcnt(0)
	s_add_i32 s31, s2, s31
	s_cmpk_lt_i32 s31, 0x580
	s_cselect_b64 s[10:11], -1, 0
	s_and_b64 vcc, exec, s[10:11]
	v_mov_b32_e32 v54, 0
	v_mov_b32_e32 v55, 0
	v_mov_b32_e32 v56, 0
	v_mov_b32_e32 v57, 0
	s_cbranch_vccz .LBB0_433
	s_ashr_i32 s2, s31, 31
	s_lshr_b32 s2, s2, 29
	s_add_i32 s2, s31, s2
	s_ashr_i32 s8, s2, 3
	s_and_b32 s2, s2, -8
	s_sub_i32 s2, s31, s2
	s_cmp_lt_i32 s2, 0
	s_cselect_b32 s9, s73, 0xb0
	s_mul_i32 s2, s9, s2
	s_add_i32 s2, s2, s8
	s_mul_hi_i32 s8, s2, 0x2e8ba2e9
	s_lshr_b32 s9, s8, 31
	s_ashr_i32 s8, s8, 4
	s_add_i32 s8, s8, s9
	s_mul_i32 s9, s8, 0x58
	s_sub_i32 s2, s2, s9
	s_bfe_i32 s9, s2, 0x80000
	s_bfe_u32 s9, s9, 0x2000d
	s_add_i32 s9, s2, s9
	s_bfe_i32 s13, s9, 0x80000
	s_and_b32 s9, s9, 0xfc
	s_sub_i32 s2, s2, s9
	s_sext_i32_i8 s2, s2
	s_lshl_b32 s8, s8, 10
	s_lshl_b32 s2, s2, 8
	s_sext_i32_i16 s13, s13
	s_add_i32 s8, s2, s8
	s_lshl_b32 s2, s13, 6
	s_ashr_i32 s9, s8, 31
	s_and_b32 s34, s2, 0xffffff00
	v_add_u32_e32 v50, s8, v203
	s_lshl_b64 s[8:9], s[8:9], 11
	s_add_u32 s64, s94, s8
	s_addc_u32 s2, s95, s9
	s_ashr_i32 s35, s34, 31
	v_ashrrev_i32_e32 v51, 31, v50
	s_lshl_b64 s[8:9], s[34:35], 11
	v_lshlrev_b64 v[50:51], 6, v[50:51]
	s_add_u32 s36, s18, s8
	s_mov_b32 m0, s22
	v_lshl_add_u64 v[54:55], v[172:173], 0, v[50:51]
	s_addc_u32 s8, s19, s9
	s_and_b32 s65, s2, 0xffff
	global_load_dwordx4 v[50:53], v[54:55], off
	s_nop 0
	global_load_dwordx4 v[54:57], v[54:55], off offset:16
	s_and_b32 s37, s8, 0xffff
	s_mov_b32 s38, s66
	s_mov_b32 s39, s67
	buffer_load_dwordx4 v201, s[64:67], 0 offen lds
	s_mov_b32 m0, s23
	s_nop 0
	buffer_load_dwordx4 v201, s[36:39], 0 offen lds
	s_mov_b32 m0, s24
	s_nop 0
	buffer_load_dwordx4 v201, s[64:67], s67 offen lds
	s_mov_b32 m0, s25
	s_nop 0
	buffer_load_dwordx4 v201, s[36:39], s67 offen lds
	s_mov_b32 m0, s26
	s_nop 0
	buffer_load_dwordx4 v201, s[64:67], s83 offen lds
	s_mov_b32 m0, s27
	s_nop 0
	buffer_load_dwordx4 v201, s[36:39], s83 offen lds
	s_mov_b32 m0, s28
	s_nop 0
	buffer_load_dwordx4 v201, s[64:67], s90 offen lds
	s_mov_b32 m0, s29
	s_nop 0
	buffer_load_dwordx4 v201, s[36:39], s90 offen lds

.LBB0_564:
	s_and_b64 vcc, exec, s[8:9]
	s_cbranch_vccz .LBB0_563
	s_nop 0
	v_mul_f32_e32 v150, v150, v166
	v_mul_f32_e32 v176, 0xbfb8aa3b, v150
	v_exp_f32_e32 v176, v176
	v_mul_f32_e32 v154, v154, v166
	v_mul_f32_e32 v142, v142, v166
	v_mul_f32_e32 v146, v146, v166
	v_add_f32_e32 v176, 1.0, v176
	v_rcp_f32_e32 v176, v176
	s_nop 0
	v_mul_f32_e32 v150, v150, v176
	v_mul_f32_e32 v150, v154, v150
	v_cvt_pk_bf16_f32 v150, v150, v1
	global_store_short v[174:175], v150, off
	v_mul_f32_e32 v150, 0xbfb8aa3b, v142
	v_exp_f32_e32 v150, v150
	s_nop 0
	v_add_f32_e32 v150, 1.0, v150
	v_rcp_f32_e32 v150, v150
	s_nop 0
	v_mul_f32_e32 v142, v142, v150
	v_mul_f32_e32 v142, v146, v142
	v_cvt_pk_bf16_f32 v142, v142, v1
	global_store_short v[174:175], v142, off offset:32
	v_lshl_add_u64 v[174:175], v[174:175], 0, s[98:99]
	v_mul_f32_e32 v142, v151, v167
	v_mul_f32_e32 v150, 0xbfb8aa3b, v142
	v_exp_f32_e32 v150, v150
	v_mul_f32_e32 v146, v155, v167
	v_add_f32_e32 v150, 1.0, v150
	v_rcp_f32_e32 v150, v150
	s_nop 0
	v_mul_f32_e32 v142, v142, v150
	v_mul_f32_e32 v142, v146, v142
	v_cvt_pk_bf16_f32 v142, v142, v1
	global_store_short v[174:175], v142, off
	v_mul_f32_e32 v142, v143, v167
	v_mul_f32_e32 v146, 0xbfb8aa3b, v142
	v_exp_f32_e32 v146, v146
	v_mul_f32_e32 v143, v147, v167
	v_add_f32_e32 v146, 1.0, v146
	v_rcp_f32_e32 v146, v146
	s_nop 0
	v_mul_f32_e32 v142, v142, v146
	v_mul_f32_e32 v142, v143, v142
	v_cvt_pk_bf16_f32 v142, v142, v1
	global_store_short v[174:175], v142, off offset:32
	v_lshl_add_u64 v[142:143], v[174:175], 0, s[98:99]
	v_mul_f32_e32 v146, v152, v168
	v_mul_f32_e32 v150, 0xbfb8aa3b, v146
	v_exp_f32_e32 v150, v150
	v_mul_f32_e32 v147, v156, v168
	v_mul_f32_e32 v144, v144, v168
	v_add_f32_e32 v150, 1.0, v150
	v_rcp_f32_e32 v150, v150
	s_nop 0
	v_mul_f32_e32 v146, v146, v150
	v_mul_f32_e32 v146, v147, v146
	v_mul_f32_e32 v147, 0xbfb8aa3b, v144
	v_exp_f32_e32 v147, v147
	v_cvt_pk_bf16_f32 v146, v146, v1
	global_store_short v[142:143], v146, off
	v_mul_f32_e32 v146, v148, v168
	v_add_f32_e32 v147, 1.0, v147
	v_rcp_f32_e32 v147, v147
	s_nop 0
	v_mul_f32_e32 v144, v144, v147
	v_mul_f32_e32 v144, v146, v144
	v_cvt_pk_bf16_f32 v144, v144, v1
	global_store_short v[142:143], v144, off offset:32
	v_lshl_add_u64 v[142:143], v[142:143], 0, s[98:99]
	v_mul_f32_e32 v144, v153, v169
	v_mul_f32_e32 v147, 0xbfb8aa3b, v144
	v_exp_f32_e32 v147, v147
	v_mul_f32_e32 v146, v157, v169
	v_add_f32_e32 v147, 1.0, v147
	v_rcp_f32_e32 v147, v147
	s_nop 0
	v_mul_f32_e32 v144, v144, v147
	v_mul_f32_e32 v144, v146, v144
	v_cvt_pk_bf16_f32 v144, v144, v1
	global_store_short v[142:143], v144, off
	v_mul_f32_e32 v144, v145, v169
	v_mul_f32_e32 v146, 0xbfb8aa3b, v144
	v_exp_f32_e32 v146, v146
	v_mul_f32_e32 v145, v149, v169
	v_add_f32_e32 v146, 1.0, v146
	v_rcp_f32_e32 v146, v146
	s_nop 0
	v_mul_f32_e32 v144, v144, v146
	v_mul_f32_e32 v144, v145, v144
	v_cvt_pk_bf16_f32 v144, v144, v1
	global_store_short v[142:143], v144, off offset:32
	v_lshl_add_u64 v[142:143], v[142:143], 0, s[98:99]
	v_mul_f32_e32 v130, v130, v162
	v_mul_f32_e32 v144, 0xbfb8aa3b, v130
	v_exp_f32_e32 v144, v144
	v_mul_f32_e32 v134, v134, v162
	v_lshl_add_u64 v[142:143], v[142:143], 0, s[44:45]
	v_mul_f32_e32 v122, v122, v162
	v_add_f32_e32 v144, 1.0, v144
	v_rcp_f32_e32 v144, v144
	v_mul_f32_e32 v126, v126, v162
	v_mul_f32_e32 v130, v130, v144
	v_mul_f32_e32 v130, v134, v130
	v_cvt_pk_bf16_f32 v130, v130, v1
	global_store_short v[142:143], v130, off
	v_mul_f32_e32 v130, 0xbfb8aa3b, v122
	v_exp_f32_e32 v130, v130
	s_nop 0
	v_add_f32_e32 v130, 1.0, v130
	v_rcp_f32_e32 v130, v130
	s_nop 0
	v_mul_f32_e32 v122, v122, v130
	v_mul_f32_e32 v122, v126, v122
	v_cvt_pk_bf16_f32 v122, v122, v1
	global_store_short v[142:143], v122, off offset:32
	v_lshl_add_u64 v[142:143], v[142:143], 0, s[98:99]
	v_mul_f32_e32 v122, v131, v163
	v_mul_f32_e32 v130, 0xbfb8aa3b, v122
	v_exp_f32_e32 v130, v130
	v_mul_f32_e32 v126, v135, v163
	v_add_f32_e32 v130, 1.0, v130
	v_rcp_f32_e32 v130, v130
	s_nop 0
	v_mul_f32_e32 v122, v122, v130
	v_mul_f32_e32 v122, v126, v122
	v_cvt_pk_bf16_f32 v122, v122, v1
	global_store_short v[142:143], v122, off
	v_mul_f32_e32 v122, v123, v163
	v_mul_f32_e32 v126, 0xbfb8aa3b, v122
	v_exp_f32_e32 v126, v126
	v_mul_f32_e32 v123, v127, v163
	v_add_f32_e32 v126, 1.0, v126
	v_rcp_f32_e32 v126, v126
	s_nop 0
	v_mul_f32_e32 v122, v122, v126
	v_mul_f32_e32 v122, v123, v122
	v_cvt_pk_bf16_f32 v122, v122, v1
	global_store_short v[142:143], v122, off offset:32
	v_lshl_add_u64 v[122:123], v[142:143], 0, s[98:99]
	v_mul_f32_e32 v126, v132, v164
	v_mul_f32_e32 v130, 0xbfb8aa3b, v126
	v_exp_f32_e32 v130, v130
	v_mul_f32_e32 v127, v136, v164
	v_mul_f32_e32 v124, v124, v164
	v_add_f32_e32 v130, 1.0, v130
	v_rcp_f32_e32 v130, v130
	s_nop 0
	v_mul_f32_e32 v126, v126, v130
	v_mul_f32_e32 v126, v127, v126
	v_mul_f32_e32 v127, 0xbfb8aa3b, v124
	v_exp_f32_e32 v127, v127
	v_cvt_pk_bf16_f32 v126, v126, v1
	global_store_short v[122:123], v126, off
	v_mul_f32_e32 v126, v128, v164
	v_add_f32_e32 v127, 1.0, v127
	v_rcp_f32_e32 v127, v127
	s_nop 0
	v_mul_f32_e32 v124, v124, v127
	v_mul_f32_e32 v124, v126, v124
	v_cvt_pk_bf16_f32 v124, v124, v1
	global_store_short v[122:123], v124, off offset:32
	v_lshl_add_u64 v[122:123], v[122:123], 0, s[98:99]
	v_mul_f32_e32 v124, v133, v165
	v_mul_f32_e32 v127, 0xbfb8aa3b, v124
	v_exp_f32_e32 v127, v127
	v_mul_f32_e32 v126, v137, v165
	v_add_f32_e32 v127, 1.0, v127
	v_rcp_f32_e32 v127, v127
	s_nop 0
	v_mul_f32_e32 v124, v124, v127
	v_mul_f32_e32 v124, v126, v124
	v_cvt_pk_bf16_f32 v124, v124, v1
	global_store_short v[122:123], v124, off
	v_mul_f32_e32 v124, v125, v165
	v_mul_f32_e32 v126, 0xbfb8aa3b, v124
	v_exp_f32_e32 v126, v126
	v_mul_f32_e32 v125, v129, v165
	v_add_f32_e32 v126, 1.0, v126
	v_rcp_f32_e32 v126, v126
	s_nop 0
	v_mul_f32_e32 v124, v124, v126
	v_mul_f32_e32 v124, v125, v124
	v_cvt_pk_bf16_f32 v124, v124, v1
	global_store_short v[122:123], v124, off offset:32
	v_lshl_add_u64 v[122:123], v[122:123], 0, s[98:99]
	v_mul_f32_e32 v110, v110, v158
	v_mul_f32_e32 v124, 0xbfb8aa3b, v110
	v_exp_f32_e32 v124, v124
	v_mul_f32_e32 v114, v114, v158
	v_lshl_add_u64 v[122:123], v[122:123], 0, s[44:45]
	v_mul_f32_e32 v102, v102, v158
	v_add_f32_e32 v124, 1.0, v124
	v_rcp_f32_e32 v124, v124
	v_mul_f32_e32 v106, v106, v158
	v_mul_f32_e32 v110, v110, v124
	v_mul_f32_e32 v110, v114, v110
	v_cvt_pk_bf16_f32 v110, v110, v1
	global_store_short v[122:123], v110, off
	v_mul_f32_e32 v110, 0xbfb8aa3b, v102
	v_exp_f32_e32 v110, v110
	s_nop 0
	v_add_f32_e32 v110, 1.0, v110
	v_rcp_f32_e32 v110, v110
	s_nop 0
	v_mul_f32_e32 v102, v102, v110
	v_mul_f32_e32 v102, v106, v102
	v_cvt_pk_bf16_f32 v102, v102, v1
	global_store_short v[122:123], v102, off offset:32
	v_lshl_add_u64 v[122:123], v[122:123], 0, s[98:99]
	v_mul_f32_e32 v102, v111, v159
	v_mul_f32_e32 v110, 0xbfb8aa3b, v102
	v_exp_f32_e32 v110, v110
	v_mul_f32_e32 v106, v115, v159
	v_add_f32_e32 v110, 1.0, v110
	v_rcp_f32_e32 v110, v110
	s_nop 0
	v_mul_f32_e32 v102, v102, v110
	v_mul_f32_e32 v102, v106, v102
	v_cvt_pk_bf16_f32 v102, v102, v1
	global_store_short v[122:123], v102, off
	v_mul_f32_e32 v102, v103, v159
	v_mul_f32_e32 v106, 0xbfb8aa3b, v102
	v_exp_f32_e32 v106, v106
	v_mul_f32_e32 v103, v107, v159
	v_add_f32_e32 v106, 1.0, v106
	v_rcp_f32_e32 v106, v106
	s_nop 0
	v_mul_f32_e32 v102, v102, v106
	v_mul_f32_e32 v102, v103, v102
	v_cvt_pk_bf16_f32 v102, v102, v1
	global_store_short v[122:123], v102, off offset:32
	v_lshl_add_u64 v[102:103], v[122:123], 0, s[98:99]
	v_mul_f32_e32 v106, v112, v160
	v_mul_f32_e32 v110, 0xbfb8aa3b, v106
	v_exp_f32_e32 v110, v110
	v_mul_f32_e32 v107, v116, v160
	v_mul_f32_e32 v104, v104, v160
	v_add_f32_e32 v110, 1.0, v110
	v_rcp_f32_e32 v110, v110
	s_nop 0
	v_mul_f32_e32 v106, v106, v110
	v_mul_f32_e32 v106, v107, v106
	v_mul_f32_e32 v107, 0xbfb8aa3b, v104
	v_exp_f32_e32 v107, v107
	v_cvt_pk_bf16_f32 v106, v106, v1
	global_store_short v[102:103], v106, off
	v_mul_f32_e32 v106, v108, v160
	v_add_f32_e32 v107, 1.0, v107
	v_rcp_f32_e32 v107, v107
	s_nop 0
	v_mul_f32_e32 v104, v104, v107
	v_mul_f32_e32 v104, v106, v104
	v_cvt_pk_bf16_f32 v104, v104, v1
	global_store_short v[102:103], v104, off offset:32
	v_lshl_add_u64 v[102:103], v[102:103], 0, s[98:99]
	v_mul_f32_e32 v104, v113, v161
	v_mul_f32_e32 v107, 0xbfb8aa3b, v104
	v_exp_f32_e32 v107, v107
	v_mul_f32_e32 v106, v117, v161
	v_add_f32_e32 v107, 1.0, v107
	v_rcp_f32_e32 v107, v107
	s_nop 0
	v_mul_f32_e32 v104, v104, v107
	v_mul_f32_e32 v104, v106, v104
	v_cvt_pk_bf16_f32 v104, v104, v1
	global_store_short v[102:103], v104, off
	v_mul_f32_e32 v104, v105, v161
	v_mul_f32_e32 v106, 0xbfb8aa3b, v104
	v_exp_f32_e32 v106, v106
	v_mul_f32_e32 v105, v109, v161
	v_add_f32_e32 v106, 1.0, v106
	v_rcp_f32_e32 v106, v106
	s_nop 0
	v_mul_f32_e32 v104, v104, v106
	v_mul_f32_e32 v104, v105, v104
	v_cvt_pk_bf16_f32 v104, v104, v1
	global_store_short v[102:103], v104, off offset:32
	v_lshl_add_u64 v[102:103], v[102:103], 0, s[98:99]
	v_mul_f32_e32 v90, v90, v138
	v_mul_f32_e32 v104, 0xbfb8aa3b, v90
	v_exp_f32_e32 v104, v104
	v_mul_f32_e32 v94, v94, v138
	v_lshl_add_u64 v[102:103], v[102:103], 0, s[44:45]
	v_mul_f32_e32 v82, v82, v138
	v_add_f32_e32 v104, 1.0, v104
	v_rcp_f32_e32 v104, v104
	v_mul_f32_e32 v86, v86, v138
	v_mul_f32_e32 v90, v90, v104
	v_mul_f32_e32 v90, v94, v90
	v_cvt_pk_bf16_f32 v90, v90, v1
	global_store_short v[102:103], v90, off
	v_mul_f32_e32 v90, 0xbfb8aa3b, v82
	v_exp_f32_e32 v90, v90
	s_nop 0
	v_add_f32_e32 v90, 1.0, v90
	v_rcp_f32_e32 v90, v90
	s_nop 0
	v_mul_f32_e32 v82, v82, v90
	v_mul_f32_e32 v82, v86, v82
	v_cvt_pk_bf16_f32 v82, v82, v1
	global_store_short v[102:103], v82, off offset:32
	v_lshl_add_u64 v[102:103], v[102:103], 0, s[98:99]
	v_mul_f32_e32 v82, v91, v139
	v_mul_f32_e32 v90, 0xbfb8aa3b, v82
	v_exp_f32_e32 v90, v90
	v_mul_f32_e32 v86, v95, v139
	v_add_f32_e32 v90, 1.0, v90
	v_rcp_f32_e32 v90, v90
	s_nop 0
	v_mul_f32_e32 v82, v82, v90
	v_mul_f32_e32 v82, v86, v82
	v_cvt_pk_bf16_f32 v82, v82, v1
	global_store_short v[102:103], v82, off
	v_mul_f32_e32 v82, v83, v139
	v_mul_f32_e32 v86, 0xbfb8aa3b, v82
	v_exp_f32_e32 v86, v86
	v_mul_f32_e32 v83, v87, v139
	v_add_f32_e32 v86, 1.0, v86
	v_rcp_f32_e32 v86, v86
	s_nop 0
	v_mul_f32_e32 v82, v82, v86
	v_mul_f32_e32 v82, v83, v82
	v_cvt_pk_bf16_f32 v82, v82, v1
	global_store_short v[102:103], v82, off offset:32
	v_lshl_add_u64 v[82:83], v[102:103], 0, s[98:99]
	v_mul_f32_e32 v86, v92, v140
	v_mul_f32_e32 v90, 0xbfb8aa3b, v86
	v_exp_f32_e32 v90, v90
	v_mul_f32_e32 v87, v96, v140
	v_mul_f32_e32 v84, v84, v140
	v_add_f32_e32 v90, 1.0, v90
	v_rcp_f32_e32 v90, v90
	s_nop 0
	v_mul_f32_e32 v86, v86, v90
	v_mul_f32_e32 v86, v87, v86
	v_mul_f32_e32 v87, 0xbfb8aa3b, v84
	v_exp_f32_e32 v87, v87
	v_cvt_pk_bf16_f32 v86, v86, v1
	global_store_short v[82:83], v86, off
	v_mul_f32_e32 v86, v88, v140
	v_add_f32_e32 v87, 1.0, v87
	v_rcp_f32_e32 v87, v87
	s_nop 0
	v_mul_f32_e32 v84, v84, v87
	v_mul_f32_e32 v84, v86, v84
	v_cvt_pk_bf16_f32 v84, v84, v1
	global_store_short v[82:83], v84, off offset:32
	v_lshl_add_u64 v[82:83], v[82:83], 0, s[98:99]
	v_mul_f32_e32 v84, v93, v141
	v_mul_f32_e32 v87, 0xbfb8aa3b, v84
	v_exp_f32_e32 v87, v87
	v_mul_f32_e32 v86, v97, v141
	v_add_f32_e32 v87, 1.0, v87
	v_rcp_f32_e32 v87, v87
	s_nop 0
	v_mul_f32_e32 v84, v84, v87
	v_mul_f32_e32 v84, v86, v84
	v_cvt_pk_bf16_f32 v84, v84, v1
	global_store_short v[82:83], v84, off
	v_mul_f32_e32 v84, v85, v141
	v_mul_f32_e32 v86, 0xbfb8aa3b, v84
	v_exp_f32_e32 v86, v86
	v_mul_f32_e32 v85, v89, v141
	v_add_f32_e32 v86, 1.0, v86
	v_rcp_f32_e32 v86, v86
	s_nop 0
	v_mul_f32_e32 v84, v84, v86
	v_mul_f32_e32 v84, v85, v84
	v_cvt_pk_bf16_f32 v84, v84, v1
	global_store_short v[82:83], v84, off offset:32
	v_lshl_add_u64 v[82:83], v[82:83], 0, s[98:99]
	v_mul_f32_e32 v70, v70, v118
	v_mul_f32_e32 v84, 0xbfb8aa3b, v70
	v_exp_f32_e32 v84, v84
	v_mul_f32_e32 v74, v74, v118
	v_lshl_add_u64 v[82:83], v[82:83], 0, s[44:45]
	v_mul_f32_e32 v62, v62, v118
	v_add_f32_e32 v84, 1.0, v84
	v_rcp_f32_e32 v84, v84
	v_mul_f32_e32 v66, v66, v118
	v_mul_f32_e32 v70, v70, v84
	v_mul_f32_e32 v70, v74, v70
	v_cvt_pk_bf16_f32 v70, v70, v1
	global_store_short v[82:83], v70, off
	v_mul_f32_e32 v70, 0xbfb8aa3b, v62
	v_exp_f32_e32 v70, v70
	s_nop 0
	v_add_f32_e32 v70, 1.0, v70
	v_rcp_f32_e32 v70, v70
	s_nop 0
	v_mul_f32_e32 v62, v62, v70
	v_mul_f32_e32 v62, v66, v62
	v_cvt_pk_bf16_f32 v62, v62, v1
	global_store_short v[82:83], v62, off offset:32
	v_lshl_add_u64 v[82:83], v[82:83], 0, s[98:99]
	v_mul_f32_e32 v62, v71, v119
	v_mul_f32_e32 v70, 0xbfb8aa3b, v62
	v_exp_f32_e32 v70, v70
	v_mul_f32_e32 v66, v75, v119
	v_add_f32_e32 v70, 1.0, v70
	v_rcp_f32_e32 v70, v70
	s_nop 0
	v_mul_f32_e32 v62, v62, v70
	v_mul_f32_e32 v62, v66, v62
	v_cvt_pk_bf16_f32 v62, v62, v1
	global_store_short v[82:83], v62, off
	v_mul_f32_e32 v62, v63, v119
	v_mul_f32_e32 v66, 0xbfb8aa3b, v62
	v_exp_f32_e32 v66, v66
	v_mul_f32_e32 v63, v67, v119
	v_add_f32_e32 v66, 1.0, v66
	v_rcp_f32_e32 v66, v66
	s_nop 0
	v_mul_f32_e32 v62, v62, v66
	v_mul_f32_e32 v62, v63, v62
	v_cvt_pk_bf16_f32 v62, v62, v1
	global_store_short v[82:83], v62, off offset:32
	v_lshl_add_u64 v[62:63], v[82:83], 0, s[98:99]
	v_mul_f32_e32 v66, v72, v120
	v_mul_f32_e32 v70, 0xbfb8aa3b, v66
	v_exp_f32_e32 v70, v70
	v_mul_f32_e32 v67, v76, v120
	v_mul_f32_e32 v64, v64, v120
	v_add_f32_e32 v70, 1.0, v70
	v_rcp_f32_e32 v70, v70
	s_nop 0
	v_mul_f32_e32 v66, v66, v70
	v_mul_f32_e32 v66, v67, v66
	v_mul_f32_e32 v67, 0xbfb8aa3b, v64
	v_exp_f32_e32 v67, v67
	v_cvt_pk_bf16_f32 v66, v66, v1
	global_store_short v[62:63], v66, off
	v_mul_f32_e32 v66, v68, v120
	v_add_f32_e32 v67, 1.0, v67
	v_rcp_f32_e32 v67, v67
	s_nop 0
	v_mul_f32_e32 v64, v64, v67
	v_mul_f32_e32 v64, v66, v64
	v_cvt_pk_bf16_f32 v64, v64, v1
	global_store_short v[62:63], v64, off offset:32
	v_lshl_add_u64 v[62:63], v[62:63], 0, s[98:99]
	v_mul_f32_e32 v64, v73, v121
	v_mul_f32_e32 v67, 0xbfb8aa3b, v64
	v_exp_f32_e32 v67, v67
	v_mul_f32_e32 v66, v77, v121
	v_add_f32_e32 v67, 1.0, v67
	v_rcp_f32_e32 v67, v67
	s_nop 0
	v_mul_f32_e32 v64, v64, v67
	v_mul_f32_e32 v64, v66, v64
	v_cvt_pk_bf16_f32 v64, v64, v1
	global_store_short v[62:63], v64, off
	v_mul_f32_e32 v64, v65, v121
	v_mul_f32_e32 v66, 0xbfb8aa3b, v64
	v_exp_f32_e32 v66, v66
	v_mul_f32_e32 v65, v69, v121
	v_add_f32_e32 v66, 1.0, v66
	v_rcp_f32_e32 v66, v66
	s_nop 0
	v_mul_f32_e32 v64, v64, v66
	v_mul_f32_e32 v64, v65, v64
	v_cvt_pk_bf16_f32 v64, v64, v1
	global_store_short v[62:63], v64, off offset:32
	v_lshl_add_u64 v[62:63], v[62:63], 0, s[98:99]
	v_mul_f32_e32 v42, v42, v98
	v_mul_f32_e32 v64, 0xbfb8aa3b, v42
	v_exp_f32_e32 v64, v64
	v_mul_f32_e32 v46, v46, v98
	v_lshl_add_u64 v[62:63], v[62:63], 0, s[44:45]
	v_mul_f32_e32 v34, v34, v98
	v_add_f32_e32 v64, 1.0, v64
	v_rcp_f32_e32 v64, v64
	v_mul_f32_e32 v38, v38, v98
	v_mul_f32_e32 v42, v42, v64
	v_mul_f32_e32 v42, v46, v42
	v_cvt_pk_bf16_f32 v42, v42, v1
	global_store_short v[62:63], v42, off
	v_mul_f32_e32 v42, 0xbfb8aa3b, v34
	v_exp_f32_e32 v42, v42
	s_nop 0
	v_add_f32_e32 v42, 1.0, v42
	v_rcp_f32_e32 v42, v42
	s_nop 0
	v_mul_f32_e32 v34, v34, v42
	v_mul_f32_e32 v34, v38, v34
	v_cvt_pk_bf16_f32 v34, v34, v1
	global_store_short v[62:63], v34, off offset:32
	v_lshl_add_u64 v[62:63], v[62:63], 0, s[98:99]
	v_mul_f32_e32 v34, v43, v99
	v_mul_f32_e32 v42, 0xbfb8aa3b, v34
	v_exp_f32_e32 v42, v42
	v_mul_f32_e32 v38, v47, v99
	v_add_f32_e32 v42, 1.0, v42
	v_rcp_f32_e32 v42, v42
	s_nop 0
	v_mul_f32_e32 v34, v34, v42
	v_mul_f32_e32 v34, v38, v34
	v_cvt_pk_bf16_f32 v34, v34, v1
	global_store_short v[62:63], v34, off
	v_mul_f32_e32 v34, v35, v99
	v_mul_f32_e32 v38, 0xbfb8aa3b, v34
	v_exp_f32_e32 v38, v38
	v_mul_f32_e32 v35, v39, v99
	v_add_f32_e32 v38, 1.0, v38
	v_rcp_f32_e32 v38, v38
	s_nop 0
	v_mul_f32_e32 v34, v34, v38
	v_mul_f32_e32 v34, v35, v34
	v_cvt_pk_bf16_f32 v34, v34, v1
	global_store_short v[62:63], v34, off offset:32
	v_lshl_add_u64 v[34:35], v[62:63], 0, s[98:99]
	v_mul_f32_e32 v38, v44, v100
	v_mul_f32_e32 v42, 0xbfb8aa3b, v38
	v_exp_f32_e32 v42, v42
	v_mul_f32_e32 v39, v48, v100
	v_mul_f32_e32 v36, v36, v100
	v_add_f32_e32 v42, 1.0, v42
	v_rcp_f32_e32 v42, v42
	s_nop 0
	v_mul_f32_e32 v38, v38, v42
	v_mul_f32_e32 v38, v39, v38
	v_mul_f32_e32 v39, 0xbfb8aa3b, v36
	v_exp_f32_e32 v39, v39
	v_cvt_pk_bf16_f32 v38, v38, v1
	global_store_short v[34:35], v38, off
	v_mul_f32_e32 v38, v40, v100
	v_add_f32_e32 v39, 1.0, v39
	v_rcp_f32_e32 v39, v39
	s_nop 0
	v_mul_f32_e32 v36, v36, v39
	v_mul_f32_e32 v36, v38, v36
	v_cvt_pk_bf16_f32 v36, v36, v1
	global_store_short v[34:35], v36, off offset:32
	v_lshl_add_u64 v[34:35], v[34:35], 0, s[98:99]
	v_mul_f32_e32 v36, v45, v101
	v_mul_f32_e32 v39, 0xbfb8aa3b, v36
	v_exp_f32_e32 v39, v39
	v_mul_f32_e32 v38, v49, v101
	v_add_f32_e32 v39, 1.0, v39
	v_rcp_f32_e32 v39, v39
	s_nop 0
	v_mul_f32_e32 v36, v36, v39
	v_mul_f32_e32 v36, v38, v36
	v_cvt_pk_bf16_f32 v36, v36, v1
	global_store_short v[34:35], v36, off
	v_mul_f32_e32 v36, v37, v101
	v_mul_f32_e32 v38, 0xbfb8aa3b, v36
	v_exp_f32_e32 v38, v38
	v_mul_f32_e32 v37, v41, v101
	v_add_f32_e32 v38, 1.0, v38
	v_rcp_f32_e32 v38, v38
	s_nop 0
	v_mul_f32_e32 v36, v36, v38
	v_mul_f32_e32 v36, v37, v36
	v_cvt_pk_bf16_f32 v36, v36, v1
	global_store_short v[34:35], v36, off offset:32
	v_lshl_add_u64 v[34:35], v[34:35], 0, s[98:99]
	v_mul_f32_e32 v26, v26, v78
	v_mul_f32_e32 v36, 0xbfb8aa3b, v26
	v_exp_f32_e32 v36, v36
	v_mul_f32_e32 v30, v30, v78
	v_lshl_add_u64 v[34:35], v[34:35], 0, s[44:45]
	v_mul_f32_e32 v18, v18, v78
	v_add_f32_e32 v36, 1.0, v36
	v_rcp_f32_e32 v36, v36
	v_mul_f32_e32 v22, v22, v78
	v_mul_f32_e32 v26, v26, v36
	v_mul_f32_e32 v26, v30, v26
	v_cvt_pk_bf16_f32 v26, v26, v1
	global_store_short v[34:35], v26, off
	v_mul_f32_e32 v26, 0xbfb8aa3b, v18
	v_exp_f32_e32 v26, v26
	s_nop 0
	v_add_f32_e32 v26, 1.0, v26
	v_rcp_f32_e32 v26, v26
	s_nop 0
	v_mul_f32_e32 v18, v18, v26
	v_mul_f32_e32 v18, v22, v18
	v_cvt_pk_bf16_f32 v18, v18, v1
	global_store_short v[34:35], v18, off offset:32
	v_lshl_add_u64 v[34:35], v[34:35], 0, s[98:99]
	v_mul_f32_e32 v18, v27, v79
	v_mul_f32_e32 v26, 0xbfb8aa3b, v18
	v_exp_f32_e32 v26, v26
	v_mul_f32_e32 v22, v31, v79
	v_add_f32_e32 v26, 1.0, v26
	v_rcp_f32_e32 v26, v26
	s_nop 0
	v_mul_f32_e32 v18, v18, v26
	v_mul_f32_e32 v18, v22, v18
	v_cvt_pk_bf16_f32 v18, v18, v1
	global_store_short v[34:35], v18, off
	v_mul_f32_e32 v18, v19, v79
	v_mul_f32_e32 v22, 0xbfb8aa3b, v18
	v_exp_f32_e32 v22, v22
	v_mul_f32_e32 v19, v23, v79
	v_add_f32_e32 v22, 1.0, v22
	v_rcp_f32_e32 v22, v22
	s_nop 0
	v_mul_f32_e32 v18, v18, v22
	v_mul_f32_e32 v18, v19, v18
	v_cvt_pk_bf16_f32 v18, v18, v1
	global_store_short v[34:35], v18, off offset:32
	v_lshl_add_u64 v[18:19], v[34:35], 0, s[98:99]
	v_mul_f32_e32 v22, v28, v80
	v_mul_f32_e32 v26, 0xbfb8aa3b, v22
	v_exp_f32_e32 v26, v26
	v_mul_f32_e32 v23, v32, v80
	v_mul_f32_e32 v20, v20, v80
	v_add_f32_e32 v26, 1.0, v26
	v_rcp_f32_e32 v26, v26
	s_nop 0
	v_mul_f32_e32 v22, v22, v26
	v_mul_f32_e32 v22, v23, v22
	v_mul_f32_e32 v23, 0xbfb8aa3b, v20
	v_exp_f32_e32 v23, v23
	v_cvt_pk_bf16_f32 v22, v22, v1
	global_store_short v[18:19], v22, off
	v_mul_f32_e32 v22, v24, v80
	v_add_f32_e32 v23, 1.0, v23
	v_rcp_f32_e32 v23, v23
	s_nop 0
	v_mul_f32_e32 v20, v20, v23
	v_mul_f32_e32 v20, v22, v20
	v_cvt_pk_bf16_f32 v20, v20, v1
	global_store_short v[18:19], v20, off offset:32
	v_lshl_add_u64 v[18:19], v[18:19], 0, s[98:99]
	v_mul_f32_e32 v20, v29, v81
	v_mul_f32_e32 v23, 0xbfb8aa3b, v20
	v_exp_f32_e32 v23, v23
	v_mul_f32_e32 v22, v33, v81
	v_add_f32_e32 v23, 1.0, v23
	v_rcp_f32_e32 v23, v23
	s_nop 0
	v_mul_f32_e32 v20, v20, v23
	v_mul_f32_e32 v20, v22, v20
	v_cvt_pk_bf16_f32 v20, v20, v1
	global_store_short v[18:19], v20, off
	v_mul_f32_e32 v20, v21, v81
	v_mul_f32_e32 v22, 0xbfb8aa3b, v20
	v_exp_f32_e32 v22, v22
	v_mul_f32_e32 v21, v25, v81
	v_add_f32_e32 v22, 1.0, v22
	v_rcp_f32_e32 v22, v22
	s_nop 0
	v_mul_f32_e32 v20, v20, v22
	v_mul_f32_e32 v20, v21, v20
	v_cvt_pk_bf16_f32 v20, v20, v1
	global_store_short v[18:19], v20, off offset:32
	v_lshl_add_u64 v[18:19], v[18:19], 0, s[98:99]
	v_mul_f32_e32 v10, v10, v58
	v_mul_f32_e32 v20, 0xbfb8aa3b, v10
	v_exp_f32_e32 v20, v20
	v_mul_f32_e32 v14, v14, v58
	v_lshl_add_u64 v[18:19], v[18:19], 0, s[44:45]
	v_mul_f32_e32 v2, v2, v58
	v_add_f32_e32 v20, 1.0, v20
	v_rcp_f32_e32 v20, v20
	v_mul_f32_e32 v6, v6, v58
	v_mul_f32_e32 v10, v10, v20
	v_mul_f32_e32 v10, v14, v10
	v_cvt_pk_bf16_f32 v10, v10, v1
	global_store_short v[18:19], v10, off
	v_mul_f32_e32 v10, 0xbfb8aa3b, v2
	v_exp_f32_e32 v10, v10
	s_nop 0
	v_add_f32_e32 v10, 1.0, v10
	v_rcp_f32_e32 v10, v10
	s_nop 0
	v_mul_f32_e32 v2, v2, v10
	v_mul_f32_e32 v2, v6, v2
	v_cvt_pk_bf16_f32 v2, v2, v1
	global_store_short v[18:19], v2, off offset:32
	v_lshl_add_u64 v[18:19], v[18:19], 0, s[98:99]
	v_mul_f32_e32 v2, v11, v59
	v_mul_f32_e32 v10, 0xbfb8aa3b, v2
	v_exp_f32_e32 v10, v10
	v_mul_f32_e32 v6, v15, v59
	v_add_f32_e32 v10, 1.0, v10
	v_rcp_f32_e32 v10, v10
	s_nop 0
	v_mul_f32_e32 v2, v2, v10
	v_mul_f32_e32 v2, v6, v2
	v_cvt_pk_bf16_f32 v2, v2, v1
	global_store_short v[18:19], v2, off
	v_mul_f32_e32 v2, v3, v59
	v_mul_f32_e32 v6, 0xbfb8aa3b, v2
	v_exp_f32_e32 v6, v6
	v_mul_f32_e32 v3, v7, v59
	v_add_f32_e32 v6, 1.0, v6
	v_rcp_f32_e32 v6, v6
	s_nop 0
	v_mul_f32_e32 v2, v2, v6
	v_mul_f32_e32 v2, v3, v2
	v_cvt_pk_bf16_f32 v2, v2, v1
	global_store_short v[18:19], v2, off offset:32
	v_lshl_add_u64 v[2:3], v[18:19], 0, s[98:99]
	v_mul_f32_e32 v6, v12, v60
	v_mul_f32_e32 v10, 0xbfb8aa3b, v6
	v_exp_f32_e32 v10, v10
	v_mul_f32_e32 v7, v16, v60
	v_mul_f32_e32 v4, v4, v60
	v_add_f32_e32 v10, 1.0, v10
	v_rcp_f32_e32 v10, v10
	s_nop 0
	v_mul_f32_e32 v6, v6, v10
	v_mul_f32_e32 v6, v7, v6
	v_mul_f32_e32 v7, 0xbfb8aa3b, v4
	v_exp_f32_e32 v7, v7
	v_cvt_pk_bf16_f32 v6, v6, v1
	global_store_short v[2:3], v6, off
	v_mul_f32_e32 v6, v8, v60
	v_add_f32_e32 v7, 1.0, v7
	v_rcp_f32_e32 v7, v7
	s_nop 0
	v_mul_f32_e32 v4, v4, v7
	v_mul_f32_e32 v4, v6, v4
	v_cvt_pk_bf16_f32 v4, v4, v1
	global_store_short v[2:3], v4, off offset:32
	v_lshl_add_u64 v[2:3], v[2:3], 0, s[98:99]
	v_mul_f32_e32 v4, v13, v61
	v_mul_f32_e32 v7, 0xbfb8aa3b, v4
	v_exp_f32_e32 v7, v7
	v_mul_f32_e32 v6, v17, v61
	v_add_f32_e32 v7, 1.0, v7
	v_rcp_f32_e32 v7, v7
	s_nop 0
	v_mul_f32_e32 v4, v4, v7
	v_mul_f32_e32 v4, v6, v4
	v_cvt_pk_bf16_f32 v4, v4, v1
	global_store_short v[2:3], v4, off
	v_mul_f32_e32 v4, v5, v61
	v_mul_f32_e32 v6, 0xbfb8aa3b, v4
	v_exp_f32_e32 v6, v6
	v_mul_f32_e32 v5, v9, v61
	v_add_f32_e32 v6, 1.0, v6
	v_rcp_f32_e32 v6, v6
	s_nop 0
	v_mul_f32_e32 v4, v4, v6
	v_mul_f32_e32 v4, v5, v4
	v_cvt_pk_bf16_f32 v4, v4, v1
	global_store_short v[2:3], v4, off offset:32
	v_lshl_add_u64 v[2:3], v[2:3], 0, s[98:99]
	s_nop 0
	v_lshl_add_u64 v[2:3], v[2:3], 0, s[44:45]
	s_andn2_b64 vcc, exec, s[10:11]
	s_mov_b64 s[8:9], -1
	s_cbranch_vccnz .LBB0_422

	.amdhsa_kernel _Z11mega_kernel6Paramsiii
		.amdhsa_group_segment_fixed_size 135184
		.amdhsa_private_segment_fixed_size 0
		.amdhsa_kernarg_size 488
		.amdhsa_user_sgpr_count 2
		.amdhsa_user_sgpr_dispatch_ptr 0
		.amdhsa_user_sgpr_queue_ptr 0
		.amdhsa_user_sgpr_kernarg_segment_ptr 1
		.amdhsa_user_sgpr_dispatch_id 0
		.amdhsa_user_sgpr_kernarg_preload_length 0
		.amdhsa_user_sgpr_kernarg_preload_offset 0
		.amdhsa_user_sgpr_private_segment_size 0
		.amdhsa_uses_dynamic_stack 0
		.amdhsa_enable_private_segment 0
		.amdhsa_system_sgpr_workgroup_id_x 1
		.amdhsa_system_sgpr_workgroup_id_y 0
		.amdhsa_system_sgpr_workgroup_id_z 0
		.amdhsa_system_sgpr_workgroup_info 0
		.amdhsa_system_vgpr_workitem_id 2
		.amdhsa_next_free_vgpr 256
		.amdhsa_next_free_sgpr 100
		.amdhsa_accum_offset 256
		.amdhsa_reserve_vcc 1
		.amdhsa_float_round_mode_32 0
		.amdhsa_float_round_mode_16_64 0
		.amdhsa_float_denorm_mode_32 3
		.amdhsa_float_denorm_mode_16_64 3
		.amdhsa_dx10_clamp 1
		.amdhsa_ieee_mode 1
		.amdhsa_fp16_overflow 0
		.amdhsa_tg_split 0
		.amdhsa_exception_fp_ieee_invalid_op 0
		.amdhsa_exception_fp_denorm_src 0
		.amdhsa_exception_fp_ieee_div_zero 0
		.amdhsa_exception_fp_ieee_overflow 0
		.amdhsa_exception_fp_ieee_underflow 0
		.amdhsa_exception_fp_ieee_inexact 0
		.amdhsa_exception_int_div_zero 0
	.end_amdhsa_kernel

.Lfunc_end0:
	.size	_Z11mega_kernel6Paramsiii, .Lfunc_end0-_Z11mega_kernel6Paramsiii
	.set _Z11mega_kernel6Paramsiii.num_vgpr, 256
	.set _Z11mega_kernel6Paramsiii.num_agpr, 0
	.set _Z11mega_kernel6Paramsiii.numbered_sgpr, 100
	.set _Z11mega_kernel6Paramsiii.num_named_barrier, 0
	.set _Z11mega_kernel6Paramsiii.private_seg_size, 0
	.set _Z11mega_kernel6Paramsiii.uses_vcc, 1
	.set _Z11mega_kernel6Paramsiii.uses_flat_scratch, 0
	.set _Z11mega_kernel6Paramsiii.has_dyn_sized_stack, 0
	.set _Z11mega_kernel6Paramsiii.has_recursion, 0
	.set _Z11mega_kernel6Paramsiii.has_indirect_call, 0

amdhsa.kernels:
  - .agpr_count:     0
    .args:
      - .offset:         0
        .size:           216
        .value_kind:     by_value
      - .offset:         216
        .size:           4
        .value_kind:     by_value
      - .offset:         220
        .size:           4
        .value_kind:     by_value
      - .offset:         224
        .size:           4
        .value_kind:     by_value
      - .offset:         232
        .size:           4
        .value_kind:     hidden_block_count_x
      - .offset:         236
        .size:           4
        .value_kind:     hidden_block_count_y
      - .offset:         240
        .size:           4
        .value_kind:     hidden_block_count_z
      - .offset:         244
        .size:           2
        .value_kind:     hidden_group_size_x
      - .offset:         246
        .size:           2
        .value_kind:     hidden_group_size_y
      - .offset:         248
        .size:           2
        .value_kind:     hidden_group_size_z
      - .offset:         250
        .size:           2
        .value_kind:     hidden_remainder_x
      - .offset:         252
        .size:           2
        .value_kind:     hidden_remainder_y
      - .offset:         254
        .size:           2
        .value_kind:     hidden_remainder_z
      - .offset:         272
        .size:           8
        .value_kind:     hidden_global_offset_x
      - .offset:         280
        .size:           8
        .value_kind:     hidden_global_offset_y
      - .offset:         288
        .size:           8
        .value_kind:     hidden_global_offset_z
      - .offset:         296
        .size:           2
        .value_kind:     hidden_grid_dims
      - .offset:         320
        .size:           8
        .value_kind:     hidden_multigrid_sync_arg
    .group_segment_fixed_size: 135184
    .kernarg_segment_align: 8
    .kernarg_segment_size: 488
    .language:       OpenCL C
    .language_version:
      - 2
      - 0
    .max_flat_workgroup_size: 512
    .name:           _Z11mega_kernel6Paramsiii
    .private_segment_fixed_size: 0
    .sgpr_count:     106
    .sgpr_spill_count: 70
    .symbol:         _Z11mega_kernel6Paramsiii.kd
    .uniform_work_group_size: 1
    .uses_dynamic_stack: false
    .vgpr_count:     256
    .vgpr_spill_count: 0
    .wavefront_size: 64
